# ret_m3: batch V-tile loads, hoist cos/sin 2nd halves, preload gate+normw, flat->global, no per-store drains
# speedup vs baseline: 1.0109x; 1.0109x over previous
; #define LAS __attribute__((address_space(3)))
; __device__ __forceinline__ float ret_lg(int h) { return log1pf(-exp2f(-5.0f - (float)h)); }
; __device__ __forceinline__ void w_store_vT(LAS bf16_t* vN, const bf16_t* src, int lane) {
; #pragma unroll
;     for (int i = 0; i < 8; ++i) { const int m = (lane >> 3) + 8 * i, e0 = 8 * (lane & 7); *(LAS u32x4*)(vN + m * LD + e0) = *(const u32x4*)(src + (size_t)m * NIN + e0); }
; }
.LBB0_187:
	s_lshr_b32 s20, s46, 8
	s_lshr_b32 s21, s46, 9
	s_add_i32 s20, s20, s46
	s_and_b32 s21, s21, 12
	s_add_i32 s20, s20, s21
	s_and_b32 s21, s20, 12
	s_cmp_lg_u32 s21, 8
	s_cbranch_scc1 .LBB0_186
	s_and_b32 s27, s20, 11
	s_ashr_i32 s20, s46, 31
	s_ashr_i32 s21, s46, 4
	s_lshr_b32 s20, s20, 25
	s_add_i32 s27, s27, -8
	s_add_i32 s24, s21, s20
	v_cvt_f32_u32_e32 v0, s27
	s_ashr_i32 s20, s24, 7
	s_and_b32 s24, s24, 0xffffff80
	s_sub_i32 s21, s21, s24
	s_lshl_b32 s24, s20, 13
	s_lshl_b32 s38, s21, 6
	s_add_i32 s34, s38, s24
	v_sub_f32_e32 v0, 0xc0a00000, v0
	s_mov_b32 s24, 0xc2fc0000
	v_cmp_gt_f32_e32 vcc, s24, v0
	s_and_b64 s[40:41], vcc, exec
	s_cselect_b32 s24, 0xffffffc0, 0
	v_cndmask_b32_e32 v1, 0, v204, vcc
	v_add_f32_e32 v0, v0, v1
	v_exp_f32_e32 v0, v0
	s_ashr_i32 s35, s34, 31
	s_mul_i32 s39, s34, 0x1800
	s_add_u32 s39, s8, s39
	v_ldexp_f32 v102, v0, s24
	v_sub_f32_e32 v2, 1.0, v102
	v_add_f32_e32 v0, -1.0, v2
	v_sub_f32_e32 v1, v0, v2
	v_add_f32_e32 v1, 1.0, v1
	v_sub_f32_e64 v0, -v102, v0
	v_add_f32_e32 v4, v0, v1
	v_frexp_mant_f32_e32 v0, v2
	v_cmp_gt_f32_e32 vcc, s77, v0
	v_cvt_f64_f32_e32 v[0:1], v2
	v_frexp_exp_i32_f64_e32 v0, v[0:1]
	v_subbrev_co_u32_e32 v10, vcc, 0, v0, vcc
	v_sub_u32_e32 v0, 0, v10
	v_ldexp_f32 v1, v2, v0
	v_add_f32_e32 v2, -1.0, v1
	v_add_f32_e32 v5, 1.0, v1
	v_ldexp_f32 v0, v4, v0
	v_add_f32_e32 v4, 1.0, v2
	v_add_f32_e32 v6, -1.0, v5
	v_sub_f32_e32 v4, v1, v4
	v_sub_f32_e32 v1, v1, v6
	v_add_f32_e32 v4, v0, v4
	v_add_f32_e32 v0, v0, v1
	v_add_f32_e32 v11, v5, v0
	v_rcp_f32_e32 v13, v11
	v_sub_f32_e32 v1, v11, v5
	v_sub_f32_e32 v12, v0, v1
	v_add_f32_e32 v1, v2, v4
	v_sub_f32_e32 v0, v1, v2
	v_mul_f32_e32 v14, v1, v13
	v_sub_f32_e32 v2, v4, v0
	v_mul_f32_e32 v4, v11, v14
	v_fma_f32 v6, v14, v11, -v4
	v_fmac_f32_e32 v6, v14, v12
	v_add_f32_e32 v0, v4, v6
	v_sub_f32_e32 v5, v1, v0
	v_pk_add_f32 v[8:9], v[0:1], v[4:5] neg_lo:[0,1] neg_hi:[0,1]
	v_mov_b32_e32 v7, v0
	v_pk_add_f32 v[0:1], v[8:9], v[6:7] neg_lo:[0,1] neg_hi:[0,1]
	s_mul_hi_i32 s24, s34, 0x1800
	v_add_f32_e32 v1, v2, v1
	v_add_f32_e32 v0, v0, v1
	v_add_f32_e32 v1, v5, v0
	v_mul_f32_e32 v2, v13, v1
	v_mul_f32_e32 v4, v11, v2
	v_fma_f32 v6, v2, v11, -v4
	v_fmac_f32_e32 v6, v2, v12
	v_sub_f32_e32 v5, v5, v1
	v_add_f32_e32 v11, v0, v5
	v_add_f32_e32 v0, v4, v6
	v_sub_f32_e32 v5, v1, v0
	v_pk_add_f32 v[8:9], v[0:1], v[4:5] neg_lo:[0,1] neg_hi:[0,1]
	v_mov_b32_e32 v7, v0
	v_pk_add_f32 v[0:1], v[8:9], v[6:7] neg_lo:[0,1] neg_hi:[0,1]
	v_mov_b32_e32 v101, v132
	v_add_f32_e32 v1, v11, v1
	v_add_f32_e32 v0, v0, v1
	v_add_f32_e32 v1, v14, v2
	v_add_f32_e32 v0, v5, v0
	v_sub_f32_e32 v4, v1, v14
	v_mul_f32_e32 v0, v13, v0
	v_sub_f32_e32 v2, v2, v4
	v_add_f32_e32 v2, v2, v0
	v_add_f32_e32 v4, v1, v2
	v_mul_f32_e32 v6, v4, v4
	v_fmamk_f32 v0, v6, 0x3e9b6dac, v201
	v_fmaak_f32 v169, v6, v0, 0x3f2aaada
	v_cvt_f32_i32_e32 v0, v10
	v_sub_f32_e32 v1, v4, v1
	v_sub_f32_e32 v1, v2, v1
	v_ldexp_f32 v2, v1, 1
	v_mul_f32_e32 v1, v4, v6
	v_pk_mul_f32 v[6:7], v[0:1], v[168:169]
	v_ldexp_f32 v5, v4, 1
	v_fma_f32 v4, v0, s94, -v6
	v_fmac_f32_e32 v4, 0xb102e308, v0
	v_pk_add_f32 v[8:9], v[6:7], v[4:5]
	v_mov_b32_e32 v10, v6
	v_sub_f32_e32 v0, v9, v5
	v_sub_f32_e32 v0, v7, v0
	v_add_f32_e32 v11, v2, v0
	v_pk_add_f32 v[6:7], v[8:9], v[6:7] neg_lo:[0,1] neg_hi:[0,1]
	v_pk_add_f32 v[12:13], v[8:9], v[10:11]
	v_mov_b32_e32 v5, v8
	v_mov_b32_e32 v7, v13
	v_pk_add_f32 v[0:1], v[4:5], v[6:7] neg_lo:[0,1] neg_hi:[0,1]
	v_pk_add_f32 v[4:5], v[4:5], v[6:7]
	v_mov_b32_e32 v16, v9
	v_pk_add_f32 v[6:7], v[4:5], v[8:9] op_sel:[1,0] op_sel_hi:[0,1] neg_lo:[0,1] neg_hi:[0,1]
	v_pk_add_f32 v[14:15], v[12:13], v[6:7] op_sel_hi:[1,0] neg_lo:[0,1] neg_hi:[0,1]
	v_mov_b32_e32 v12, v13
	v_mov_b32_e32 v13, v5
	v_mov_b32_e32 v17, v6
	v_pk_add_f32 v[6:7], v[12:13], v[16:17] neg_lo:[0,1] neg_hi:[0,1]
	v_mov_b32_e32 v10, v11
	v_mov_b32_e32 v11, v8
	v_pk_add_f32 v[6:7], v[10:11], v[6:7] neg_lo:[0,1] neg_hi:[0,1]
	v_mov_b32_e32 v14, v0
	v_pk_add_f32 v[14:15], v[14:15], v[6:7]
	s_addc_u32 s43, s9, s24
	s_lshl_b32 s24, s27, 6
	s_lshl_b32 s40, s27, 7
	v_pk_add_f32 v[8:9], v[14:15], v[14:15] op_sel:[0,1] op_sel_hi:[1,0]
	s_add_u32 s42, s39, s40
	v_lshlrev_b32_e32 v2, 4, v101
	v_pk_add_f32 v[12:13], v[4:5], v[8:9] op_sel:[1,0] op_sel_hi:[0,1]
	s_addc_u32 s43, s43, 0
	v_and_b32_e32 v2, 0x70, v2
	v_mov_b32_e32 v1, v5
	v_mov_b32_e32 v15, v12
	v_mov_b32_e32 v7, v8
	v_ashrrev_i32_e32 v10, 3, v101
	v_lshl_add_u64 v[8:9], s[42:43], 0, v[2:3]
	v_pk_add_f32 v[18:19], v[14:15], v[0:1] neg_lo:[0,1] neg_hi:[0,1]
	v_mad_i64_i32 v[4:5], s[44:45], v10, s72, v[8:9]
	v_pk_add_f32 v[16:17], v[6:7], v[18:19] neg_lo:[0,1] neg_hi:[0,1]
	global_load_dwordx4 v[222:225], v[4:5], off offset:3072
	v_add_u32_e32 v4, 8, v10
	v_mad_i64_i32 v[4:5], s[44:45], v4, s72, v[8:9]
	global_load_dwordx4 v[226:229], v[4:5], off offset:3072
	v_add_u32_e32 v4, 16, v10
	v_mad_i64_i32 v[4:5], s[44:45], v4, s72, v[8:9]
	global_load_dwordx4 v[230:233], v[4:5], off offset:3072
	v_add_u32_e32 v4, 24, v10
	v_mad_i64_i32 v[4:5], s[44:45], v4, s72, v[8:9]
	global_load_dwordx4 v[234:237], v[4:5], off offset:3072
	v_add_u32_e32 v4, 32, v10
	v_mad_i64_i32 v[4:5], s[44:45], v4, s72, v[8:9]
	global_load_dwordx4 v[238:241], v[4:5], off offset:3072
	v_add_u32_e32 v4, 40, v10
	v_mad_i64_i32 v[4:5], s[44:45], v4, s72, v[8:9]
	global_load_dwordx4 v[242:245], v[4:5], off offset:3072
	v_add_u32_e32 v4, 48, v10
	v_mad_i64_i32 v[4:5], s[44:45], v4, s72, v[8:9]
	global_load_dwordx4 v[246:249], v[4:5], off offset:3072
	v_add_u32_e32 v4, 56, v10
	v_mad_i64_i32 v[4:5], s[44:45], v4, s72, v[8:9]
	global_load_dwordx4 v[250:253], v[4:5], off offset:3072
	v_mul_lo_u32 v11, v10, s23
	v_add3_u32 v2, s2, v2, v11
	v_and_b32_e32 v133, 15, v101
	v_ashrrev_i32_e32 v100, 4, v101
	s_mov_b32 s41, s25
	v_or_b32_e32 v144, 16, v133
	v_or_b32_e32 v136, 32, v133
	v_or_b32_e32 v134, 48, v133
	s_lshl_b32 s20, s20, 9
	s_lshl_b32 s21, s21, 2
	s_add_i32 s21, s21, s20
	s_or_b32 s20, s27, s21
	s_ashr_i32 s21, s20, 31
	s_lshl_b64 s[20:21], s[20:21], 13
	s_waitcnt lgkmcnt(0)
; #define LAS __attribute__((address_space(3)))
; __device__ __forceinline__ void ld8bf(const bf16_t* p, float (&o)[8]) { unpack8(*(const u32x4*)p, o); }
; __device__ __forceinline__ bf16x8 pack_frag(const float (&v)[8]) { return __builtin_bit_cast(bf16x8, pack8(v)); }
; __device__ __forceinline__ void w_store_vT(LAS bf16_t* vN, const bf16_t* src, int lane) {
; #pragma unroll
;     for (int i = 0; i < 8; ++i) { const int m = (lane >> 3) + 8 * i, e0 = 8 * (lane & 7); *(LAS u32x4*)(vN + m * LD + e0) = *(const u32x4*)(src + (size_t)m * NIN + e0); }
; }
; __device__ __forceinline__ void w_ret_m3(const Args& a, int l, unsigned char* ws, const bf16_t* proj, bf16_t* y, LAS unsigned char* wl, int b, int ck_, int h, int lane) {
;     ...
;     for (int tb = 0; tb < 4; ++tb) { const int n = 16 * tb + lo; float x1[8], x2[8], o1[8], o2[8], cs[8], sn[8];
;         const float* cp_ = cosT + (64 * ck_ + n) * 32 + 8 * fq; const float* sp_ = sinT + (64 * ck_ + n) * 32 + 8 * fq;
; #pragma unroll
;         for (int j = 0; j < 8; ++j) { cs[j] = cp_[j]; sn[j] = sp_[j]; }
;         const bf16_t* qs = proj + (size_t)(row0 + n) * NIN + C_RQ + 64 * h + 8 * fq;
;         ld8bf(qs, x1); ld8bf(qs + 32, x2);
; #pragma unroll
;         for (int j = 0; j < 8; ++j) { o1[j] = x1[j] * cs[j] - x2[j] * sn[j]; o2[j] = x2[j] * cs[j] + x1[j] * sn[j]; }
;         Qf[tb][0] = pack_frag(o1); Qf[tb][1] = pack_frag(o2);
	s_add_u32 s20, s48, s20
	s_addc_u32 s21, s49, s21
	v_cmp_gt_f32_e32 vcc, s95, v102
	v_lshlrev_b32_e32 v124, 2, v100
	v_add_u32_e32 v140, 16, v124
	v_lshlrev_b32_e32 v1, 3, v101
	v_not_b32_e32 v143, v124
	v_and_b32_e32 v1, 24, v1
	v_or_b32_e32 v141, 3, v124
	v_or_b32_e32 v142, 2, v124
	v_add_u32_e32 v104, s2, v1
	v_sub_u32_e32 v1, v133, v141
	v_cvt_f32_i32_e32 v1, v1
	v_ashrrev_i32_e32 v125, 31, v124
	v_mov_b32_e32 v186, v2
	v_lshlrev_b32_e32 v10, 3, v100
	v_ashrrev_i32_e32 v11, 31, v10
	v_or_b32_e32 v2, s38, v133
	v_lshlrev_b32_e32 v8, 5, v2
	v_lshlrev_b64 v[6:7], 2, v[10:11]
	v_ashrrev_i32_e32 v9, 31, v8
	v_lshl_add_u64 v[4:5], s[60:61], 0, v[6:7]
	v_lshl_add_u64 v[6:7], s[62:63], 0, v[6:7]
	v_lshlrev_b64 v[8:9], 2, v[8:9]
	v_lshl_add_u64 v[46:47], v[4:5], 0, v[8:9]
	v_lshl_add_u64 v[48:49], v[6:7], 0, v[8:9]
	v_or_b32_e32 v2, s34, v133
	v_mov_b64_e32 v[8:9], s[8:9]
	v_mad_i64_i32 v[20:21], s[44:45], v2, s72, v[8:9]
	v_lshl_add_u64 v[22:23], v[20:21], 0, s[40:41]
	v_lshlrev_b64 v[20:21], 1, v[10:11]
	v_lshl_add_u64 v[10:11], v[22:23], 0, v[20:21]
	global_load_dwordx4 v[22:25], v[10:11], off offset:2048
	global_load_dwordx4 v[26:29], v[10:11], off offset:2112
	global_load_dwordx4 v[30:33], v[10:11], off offset:2560
	global_load_dwordx4 v[34:37], v[10:11], off offset:2624
	global_load_dwordx4 v[38:41], v[46:47], off
	global_load_dwordx4 v[42:45], v[48:49], off
	global_load_dwordx4 v[174:177], v[46:47], off offset:16
	global_load_dwordx4 v[178:181], v[48:49], off offset:16
	s_waitcnt vmcnt(8)
	ds_write_b128 v186, v[222:225]
	ds_write_b128 v186, v[226:229] offset:1152
	ds_write_b128 v186, v[230:233] offset:2304
	ds_write_b128 v186, v[234:237] offset:3456
	ds_write_b128 v186, v[238:241] offset:4608
	ds_write_b128 v186, v[242:245] offset:5760
	ds_write_b128 v186, v[246:249] offset:6912
	ds_write_b128 v186, v[250:253] offset:8064
	v_lshlrev_b64 v[182:183], 1, v[124:125]
	v_lshl_add_u64 v[182:183], s[42:43], 0, v[182:183]
	v_mad_u64_u32 v[184:185], s[44:45], v133, s72, v[182:183]
	global_load_dwordx2 v[222:223], v[184:185], off offset:3584
	global_load_dwordx2 v[224:225], v[184:185], off offset:3616
	global_load_dwordx2 v[226:227], v[184:185], off offset:3648
	global_load_dwordx2 v[228:229], v[184:185], off offset:3680
	v_mad_u64_u32 v[184:185], s[44:45], v144, s72, v[182:183]
	global_load_dwordx2 v[230:231], v[184:185], off offset:3584
	global_load_dwordx2 v[232:233], v[184:185], off offset:3616
	global_load_dwordx2 v[234:235], v[184:185], off offset:3648
	global_load_dwordx2 v[236:237], v[184:185], off offset:3680
	v_mad_u64_u32 v[184:185], s[44:45], v136, s72, v[182:183]
	global_load_dwordx2 v[238:239], v[184:185], off offset:3584
	global_load_dwordx2 v[240:241], v[184:185], off offset:3616
	global_load_dwordx2 v[242:243], v[184:185], off offset:3648
	global_load_dwordx2 v[244:245], v[184:185], off offset:3680
	v_mad_u64_u32 v[184:185], s[44:45], v134, s72, v[182:183]
	global_load_dwordx2 v[246:247], v[184:185], off offset:3584
	global_load_dwordx2 v[248:249], v[184:185], off offset:3616
	global_load_dwordx2 v[250:251], v[184:185], off offset:3648
	global_load_dwordx2 v[252:253], v[184:185], off offset:3680
	v_or_b32_e32 v2, s38, v144
	s_waitcnt vmcnt(16) lgkmcnt(0)
	v_lshlrev_b32_e32 v10, 16, v22
	v_lshlrev_b32_e32 v50, 16, v26
	v_and_b32_e32 v51, 0xffff0000, v26
	v_and_b32_e32 v11, 0xffff0000, v22
	v_pk_mul_f32 v[52:53], v[38:39], v[50:51]
	v_pk_mul_f32 v[50:51], v[42:43], v[50:51]
	v_pk_fma_f32 v[52:53], v[42:43], v[10:11], v[52:53]
	v_pk_fma_f32 v[10:11], v[38:39], v[10:11], v[50:51] neg_lo:[0,0,1] neg_hi:[0,0,1]
	v_lshlrev_b32_e32 v50, 16, v34
	v_and_b32_e32 v51, 0xffff0000, v34
	v_cvt_pk_bf16_f32 v96, v10, v11
	v_cvt_pk_bf16_f32 v92, v52, v53
	v_lshlrev_b32_e32 v10, 16, v30
	v_and_b32_e32 v11, 0xffff0000, v30
	v_pk_mul_f32 v[52:53], v[38:39], v[50:51]
	v_lshlrev_b32_e32 v26, 16, v27
	v_pk_fma_f32 v[52:53], v[42:43], v[10:11], v[52:53]
	v_pk_mul_f32 v[42:43], v[42:43], v[50:51]
	v_and_b32_e32 v27, 0xffff0000, v27
	v_pk_fma_f32 v[10:11], v[38:39], v[10:11], v[42:43] neg_lo:[0,0,1] neg_hi:[0,0,1]
	v_lshlrev_b32_e32 v22, 16, v23
	v_and_b32_e32 v23, 0xffff0000, v23
	v_pk_mul_f32 v[38:39], v[40:41], v[26:27]
	v_pk_mul_f32 v[26:27], v[44:45], v[26:27]
	v_pk_fma_f32 v[38:39], v[44:45], v[22:23], v[38:39]
	v_pk_fma_f32 v[22:23], v[40:41], v[22:23], v[26:27] neg_lo:[0,0,1] neg_hi:[0,0,1]
	v_lshlrev_b32_e32 v26, 16, v35
	v_and_b32_e32 v27, 0xffff0000, v35
	v_cvt_pk_bf16_f32 v97, v22, v23
	v_lshlrev_b32_e32 v22, 16, v31
	v_and_b32_e32 v23, 0xffff0000, v31
	v_pk_mul_f32 v[30:31], v[40:41], v[26:27]
	v_pk_mul_f32 v[26:27], v[44:45], v[26:27]
	v_cvt_pk_bf16_f32 v93, v38, v39
	v_pk_fma_f32 v[30:31], v[44:45], v[22:23], v[30:31]
	v_pk_fma_f32 v[22:23], v[40:41], v[22:23], v[26:27] neg_lo:[0,0,1] neg_hi:[0,0,1]
	v_mov_b64_e32 v[38:39], v[174:175]
	v_mov_b64_e32 v[40:41], v[176:177]
	v_mov_b64_e32 v[42:43], v[178:179]
	v_mov_b64_e32 v[44:45], v[180:181]
	v_lshlrev_b32_e32 v34, 16, v28
	v_and_b32_e32 v35, 0xffff0000, v28
	v_lshlrev_b32_e32 v26, 16, v24
	v_and_b32_e32 v27, 0xffff0000, v24
	v_lshlrev_b32_e32 v28, 16, v29
	v_and_b32_e32 v29, 0xffff0000, v29
	v_pk_mul_f32 v[10:11], v[10:11], s[16:17] op_sel_hi:[1,0]
	v_lshlrev_b32_e32 v24, 16, v25
	v_and_b32_e32 v25, 0xffff0000, v25
	v_pk_mul_f32 v[22:23], v[22:23], s[16:17] op_sel_hi:[1,0]
	v_cvt_pk_bf16_f32 v64, v10, v11
	v_lshlrev_b32_e32 v10, 5, v2
	v_or_b32_e32 v2, s34, v144
	v_cvt_pk_bf16_f32 v65, v22, v23
	v_mad_i64_i32 v[22:23], s[44:45], v2, s72, v[8:9]
	v_ashrrev_i32_e32 v11, 31, v10
	v_lshl_add_u64 v[22:23], v[22:23], 0, s[40:41]
	v_pk_mul_f32 v[30:31], v[30:31], s[16:17] op_sel_hi:[1,0]
	v_lshlrev_b64 v[10:11], 2, v[10:11]
	v_cvt_pk_bf16_f32 v73, v30, v31
	v_or_b32_e32 v2, s38, v136
	v_pk_mul_f32 v[52:53], v[52:53], s[16:17] op_sel_hi:[1,0]
	s_waitcnt vmcnt(0) lgkmcnt(0)
; __device__ __forceinline__ void ld8bf(const bf16_t* p, float (&o)[8]) { unpack8(*(const u32x4*)p, o); }
; __device__ __forceinline__ bf16x8 pack_frag(const float (&v)[8]) { return __builtin_bit_cast(bf16x8, pack8(v)); }
; __device__ __forceinline__ void w_ret_m3(const Args& a, int l, unsigned char* ws, const bf16_t* proj, bf16_t* y, LAS unsigned char* wl, int b, int ck_, int h, int lane) {
;     ...
;     for (int tb = 0; tb < 4; ++tb) { const int n = 16 * tb + lo; float x1[8], x2[8], o1[8], o2[8], cs[8], sn[8];
;         const float* cp_ = cosT + (64 * ck_ + n) * 32 + 8 * fq; const float* sp_ = sinT + (64 * ck_ + n) * 32 + 8 * fq;
; #pragma unroll
;         for (int j = 0; j < 8; ++j) { cs[j] = cp_[j]; sn[j] = sp_[j]; }
;         const bf16_t* qs = proj + (size_t)(row0 + n) * NIN + C_RQ + 64 * h + 8 * fq;
;         ld8bf(qs, x1); ld8bf(qs + 32, x2);
; #pragma unroll
;         for (int j = 0; j < 8; ++j) { o1[j] = x1[j] * cs[j] - x2[j] * sn[j]; o2[j] = x2[j] * cs[j] + x1[j] * sn[j]; }
;         Qf[tb][0] = pack_frag(o1); Qf[tb][1] = pack_frag(o2);
;         const bf16_t* ks = proj + (size_t)(row0 + n) * NIN + C_RK + 64 * h + 8 * fq;
;         ld8bf(ks, x1); ld8bf(ks + 32, x2);
; #pragma unroll
;         for (int j = 0; j < 8; ++j) { o1[j] = (x1[j] * cs[j] - x2[j] * sn[j]) * 0.125f; o2[j] = (x2[j] * cs[j] + x1[j] * sn[j]) * 0.125f; }
;         Kf[tb][0] = pack_frag(o1); Kf[tb][1] = pack_frag(o2);
	v_pk_mul_f32 v[46:47], v[38:39], v[34:35]
	v_pk_mul_f32 v[34:35], v[42:43], v[34:35]
	v_pk_fma_f32 v[46:47], v[42:43], v[26:27], v[46:47]
	v_pk_fma_f32 v[26:27], v[38:39], v[26:27], v[34:35] neg_lo:[0,0,1] neg_hi:[0,0,1]
	v_lshlrev_b32_e32 v34, 16, v36
	v_and_b32_e32 v35, 0xffff0000, v36
	v_cvt_pk_bf16_f32 v98, v26, v27
	v_cvt_pk_bf16_f32 v94, v46, v47
	v_lshlrev_b32_e32 v26, 16, v32
	v_and_b32_e32 v27, 0xffff0000, v32
	v_pk_mul_f32 v[46:47], v[38:39], v[34:35]
	v_pk_mul_f32 v[34:35], v[42:43], v[34:35]
	v_pk_fma_f32 v[46:47], v[42:43], v[26:27], v[46:47]
	v_pk_fma_f32 v[26:27], v[38:39], v[26:27], v[34:35] neg_lo:[0,0,1] neg_hi:[0,0,1]
	v_pk_mul_f32 v[34:35], v[40:41], v[28:29]
	v_pk_mul_f32 v[28:29], v[44:45], v[28:29]
	v_pk_fma_f32 v[34:35], v[44:45], v[24:25], v[34:35]
	v_pk_fma_f32 v[24:25], v[40:41], v[24:25], v[28:29] neg_lo:[0,0,1] neg_hi:[0,0,1]
	v_lshlrev_b32_e32 v28, 16, v37
	v_and_b32_e32 v29, 0xffff0000, v37
	v_cvt_pk_bf16_f32 v99, v24, v25
	v_lshlrev_b32_e32 v24, 16, v33
	v_and_b32_e32 v25, 0xffff0000, v33
	v_pk_mul_f32 v[32:33], v[40:41], v[28:29]
	v_pk_mul_f32 v[28:29], v[44:45], v[28:29]
	v_pk_fma_f32 v[32:33], v[44:45], v[24:25], v[32:33]
	v_pk_fma_f32 v[24:25], v[40:41], v[24:25], v[28:29] neg_lo:[0,0,1] neg_hi:[0,0,1]
	v_pk_mul_f32 v[46:47], v[46:47], s[16:17] op_sel_hi:[1,0]
	v_pk_mul_f32 v[26:27], v[26:27], s[16:17] op_sel_hi:[1,0]
	v_cvt_pk_bf16_f32 v95, v34, v35
	v_pk_mul_f32 v[32:33], v[32:33], s[16:17] op_sel_hi:[1,0]
	v_pk_mul_f32 v[24:25], v[24:25], s[16:17] op_sel_hi:[1,0]
	v_lshl_add_u64 v[34:35], v[22:23], 0, v[20:21]
	v_cvt_pk_bf16_f32 v66, v26, v27
	v_cvt_pk_bf16_f32 v67, v24, v25
	v_cvt_pk_bf16_f32 v74, v46, v47
	v_cvt_pk_bf16_f32 v75, v32, v33
	v_lshl_add_u64 v[46:47], v[4:5], 0, v[10:11]
	v_lshl_add_u64 v[10:11], v[6:7], 0, v[10:11]
	global_load_dwordx4 v[22:25], v[34:35], off offset:2048
	global_load_dwordx4 v[26:29], v[34:35], off offset:2112
	global_load_dwordx4 v[30:33], v[34:35], off offset:2560
	s_nop 0
	global_load_dwordx4 v[34:37], v[34:35], off offset:2624
	s_nop 0
	global_load_dwordx2 v[42:43], v[46:47], off
	global_load_dwordx4 v[38:41], v[10:11], off
	global_load_dwordx4 v[174:177], v[46:47], off offset:8
	global_load_dwordx4 v[178:181], v[10:11], off offset:16
	global_load_dwordx2 v[182:183], v[46:47], off offset:24
	v_cvt_pk_bf16_f32 v72, v52, v53
	s_waitcnt vmcnt(0) lgkmcnt(0)
	v_lshlrev_b32_e32 v44, 16, v22
	v_lshlrev_b32_e32 v48, 16, v26
	v_and_b32_e32 v49, 0xffff0000, v26
	v_and_b32_e32 v45, 0xffff0000, v22
	v_pk_mul_f32 v[50:51], v[42:43], v[48:49]
	v_pk_mul_f32 v[48:49], v[38:39], v[48:49]
	v_pk_fma_f32 v[50:51], v[38:39], v[44:45], v[50:51]
	v_pk_fma_f32 v[44:45], v[42:43], v[44:45], v[48:49] neg_lo:[0,0,1] neg_hi:[0,0,1]
	v_lshlrev_b32_e32 v48, 16, v34
	v_and_b32_e32 v49, 0xffff0000, v34
	v_cvt_pk_bf16_f32 v88, v44, v45
	v_cvt_pk_bf16_f32 v84, v50, v51
	v_lshlrev_b32_e32 v44, 16, v30
	v_and_b32_e32 v45, 0xffff0000, v30
	v_pk_mul_f32 v[50:51], v[42:43], v[48:49]
	v_lshlrev_b32_e32 v26, 16, v27
	v_pk_fma_f32 v[50:51], v[38:39], v[44:45], v[50:51]
	v_pk_mul_f32 v[38:39], v[38:39], v[48:49]
	v_and_b32_e32 v27, 0xffff0000, v27
	v_pk_fma_f32 v[38:39], v[42:43], v[44:45], v[38:39] neg_lo:[0,0,1] neg_hi:[0,0,1]
	v_mov_b64_e32 v[42:43], v[174:175]
	v_mov_b64_e32 v[44:45], v[176:177]
	v_pk_mul_f32 v[48:49], v[38:39], s[16:17] op_sel_hi:[1,0]
	v_lshlrev_b32_e32 v22, 16, v23
	v_and_b32_e32 v23, 0xffff0000, v23
	v_pk_mul_f32 v[50:51], v[50:51], s[16:17] op_sel_hi:[1,0]
	v_cvt_pk_bf16_f32 v60, v48, v49
	v_cvt_pk_bf16_f32 v68, v50, v51
	s_waitcnt vmcnt(0) lgkmcnt(0)
	v_pk_mul_f32 v[38:39], v[42:43], v[26:27]
	v_pk_mul_f32 v[26:27], v[40:41], v[26:27]
	v_pk_fma_f32 v[38:39], v[40:41], v[22:23], v[38:39]
	v_pk_fma_f32 v[22:23], v[42:43], v[22:23], v[26:27] neg_lo:[0,0,1] neg_hi:[0,0,1]
	v_lshlrev_b32_e32 v26, 16, v35
	v_and_b32_e32 v27, 0xffff0000, v35
	v_cvt_pk_bf16_f32 v89, v22, v23
	v_lshlrev_b32_e32 v22, 16, v31
	v_and_b32_e32 v23, 0xffff0000, v31
	v_pk_mul_f32 v[30:31], v[42:43], v[26:27]
	v_cvt_pk_bf16_f32 v85, v38, v39
	v_pk_fma_f32 v[30:31], v[40:41], v[22:23], v[30:31]
	v_pk_mul_f32 v[26:27], v[40:41], v[26:27]
	v_mov_b64_e32 v[38:39], v[178:179]
	v_mov_b64_e32 v[40:41], v[180:181]
	v_pk_fma_f32 v[22:23], v[42:43], v[22:23], v[26:27] neg_lo:[0,0,1] neg_hi:[0,0,1]
	v_lshlrev_b32_e32 v26, 16, v28
	v_and_b32_e32 v27, 0xffff0000, v28
	v_lshlrev_b32_e32 v10, 16, v24
	v_and_b32_e32 v11, 0xffff0000, v24
	v_pk_mul_f32 v[34:35], v[44:45], v[26:27]
	v_lshlrev_b32_e32 v28, 16, v29
	v_and_b32_e32 v29, 0xffff0000, v29
	v_lshlrev_b32_e32 v24, 16, v25
	v_and_b32_e32 v25, 0xffff0000, v25
	v_pk_mul_f32 v[22:23], v[22:23], s[16:17] op_sel_hi:[1,0]
	v_pk_mul_f32 v[30:31], v[30:31], s[16:17] op_sel_hi:[1,0]
	v_cvt_pk_bf16_f32 v61, v22, v23
	v_cvt_pk_bf16_f32 v69, v30, v31
	s_waitcnt vmcnt(0) lgkmcnt(0)
	v_pk_mul_f32 v[26:27], v[38:39], v[26:27]
	v_pk_fma_f32 v[34:35], v[38:39], v[10:11], v[34:35]
	v_pk_fma_f32 v[10:11], v[44:45], v[10:11], v[26:27] neg_lo:[0,0,1] neg_hi:[0,0,1]
	v_lshlrev_b32_e32 v26, 16, v36
	v_and_b32_e32 v27, 0xffff0000, v36
	v_cvt_pk_bf16_f32 v90, v10, v11
	v_cvt_pk_bf16_f32 v86, v34, v35
	v_lshlrev_b32_e32 v10, 16, v32
	v_and_b32_e32 v11, 0xffff0000, v32
	v_pk_mul_f32 v[34:35], v[44:45], v[26:27]
	v_pk_mul_f32 v[26:27], v[38:39], v[26:27]
	v_pk_fma_f32 v[34:35], v[38:39], v[10:11], v[34:35]
	v_pk_fma_f32 v[10:11], v[44:45], v[10:11], v[26:27] neg_lo:[0,0,1] neg_hi:[0,0,1]
	v_mov_b64_e32 v[26:27], v[182:183]
	v_pk_mul_f32 v[10:11], v[10:11], s[16:17] op_sel_hi:[1,0]
	v_pk_mul_f32 v[34:35], v[34:35], s[16:17] op_sel_hi:[1,0]
	v_cvt_pk_bf16_f32 v62, v10, v11
	v_lshlrev_b32_e32 v10, 5, v2
	v_or_b32_e32 v2, s34, v136
	v_mad_i64_i32 v[22:23], s[44:45], v2, s72, v[8:9]
	v_ashrrev_i32_e32 v11, 31, v10
	v_lshl_add_u64 v[22:23], v[22:23], 0, s[40:41]
	v_cvt_pk_bf16_f32 v70, v34, v35
	v_lshlrev_b64 v[10:11], 2, v[10:11]
	v_lshl_add_u64 v[34:35], v[22:23], 0, v[20:21]
	v_lshl_add_u64 v[46:47], v[4:5], 0, v[10:11]
	v_lshl_add_u64 v[10:11], v[6:7], 0, v[10:11]
	v_or_b32_e32 v2, s38, v134
	s_waitcnt vmcnt(0) lgkmcnt(0)
; __device__ __forceinline__ void ld8bf(const bf16_t* p, float (&o)[8]) { unpack8(*(const u32x4*)p, o); }
; __device__ __forceinline__ bf16x8 pack_frag(const float (&v)[8]) { return __builtin_bit_cast(bf16x8, pack8(v)); }
; __device__ __forceinline__ void w_ret_m3(const Args& a, int l, unsigned char* ws, const bf16_t* proj, bf16_t* y, LAS unsigned char* wl, int b, int ck_, int h, int lane) {
;     ...
;     for (int tb = 0; tb < 4; ++tb) { const int n = 16 * tb + lo; float x1[8], x2[8], o1[8], o2[8], cs[8], sn[8];
;         const float* cp_ = cosT + (64 * ck_ + n) * 32 + 8 * fq; const float* sp_ = sinT + (64 * ck_ + n) * 32 + 8 * fq;
; #pragma unroll
;         for (int j = 0; j < 8; ++j) { cs[j] = cp_[j]; sn[j] = sp_[j]; }
;         const bf16_t* qs = proj + (size_t)(row0 + n) * NIN + C_RQ + 64 * h + 8 * fq;
;         ld8bf(qs, x1); ld8bf(qs + 32, x2);
; #pragma unroll
;         for (int j = 0; j < 8; ++j) { o1[j] = x1[j] * cs[j] - x2[j] * sn[j]; o2[j] = x2[j] * cs[j] + x1[j] * sn[j]; }
;         Qf[tb][0] = pack_frag(o1); Qf[tb][1] = pack_frag(o2);
;         const bf16_t* ks = proj + (size_t)(row0 + n) * NIN + C_RK + 64 * h + 8 * fq;
;         ld8bf(ks, x1); ld8bf(ks + 32, x2);
; #pragma unroll
;         for (int j = 0; j < 8; ++j) { o1[j] = (x1[j] * cs[j] - x2[j] * sn[j]) * 0.125f; o2[j] = (x2[j] * cs[j] + x1[j] * sn[j]) * 0.125f; }
;         Kf[tb][0] = pack_frag(o1); Kf[tb][1] = pack_frag(o2);
	v_pk_mul_f32 v[38:39], v[26:27], v[28:29]
	v_pk_mul_f32 v[28:29], v[40:41], v[28:29]
	v_pk_fma_f32 v[38:39], v[40:41], v[24:25], v[38:39]
	v_pk_fma_f32 v[24:25], v[26:27], v[24:25], v[28:29] neg_lo:[0,0,1] neg_hi:[0,0,1]
	v_lshlrev_b32_e32 v28, 16, v37
	v_and_b32_e32 v29, 0xffff0000, v37
	v_cvt_pk_bf16_f32 v91, v24, v25
	v_lshlrev_b32_e32 v24, 16, v33
	v_and_b32_e32 v25, 0xffff0000, v33
	v_pk_mul_f32 v[32:33], v[26:27], v[28:29]
	v_pk_mul_f32 v[28:29], v[40:41], v[28:29]
	v_pk_fma_f32 v[32:33], v[40:41], v[24:25], v[32:33]
	v_pk_fma_f32 v[24:25], v[26:27], v[24:25], v[28:29] neg_lo:[0,0,1] neg_hi:[0,0,1]
	v_pk_mul_f32 v[32:33], v[32:33], s[16:17] op_sel_hi:[1,0]
	v_pk_mul_f32 v[24:25], v[24:25], s[16:17] op_sel_hi:[1,0]
	v_cvt_pk_bf16_f32 v87, v38, v39
	v_cvt_pk_bf16_f32 v63, v24, v25
	v_cvt_pk_bf16_f32 v71, v32, v33
	global_load_dwordx4 v[22:25], v[34:35], off offset:2048
	global_load_dwordx4 v[26:29], v[34:35], off offset:2112
	global_load_dwordx4 v[30:33], v[34:35], off offset:2560
	s_nop 0
	global_load_dwordx4 v[34:37], v[34:35], off offset:2624
	s_nop 0
	global_load_dwordx4 v[38:41], v[46:47], off
	global_load_dwordx4 v[42:45], v[10:11], off
	global_load_dwordx4 v[174:177], v[46:47], off offset:16
	global_load_dwordx4 v[178:181], v[10:11], off offset:16
	s_waitcnt vmcnt(0) lgkmcnt(0)
	v_lshlrev_b32_e32 v48, 16, v22
	v_lshlrev_b32_e32 v50, 16, v26
	v_and_b32_e32 v51, 0xffff0000, v26
	v_and_b32_e32 v49, 0xffff0000, v22
	v_pk_mul_f32 v[52:53], v[38:39], v[50:51]
	v_pk_mul_f32 v[50:51], v[42:43], v[50:51]
	v_pk_fma_f32 v[52:53], v[42:43], v[48:49], v[52:53]
	v_pk_fma_f32 v[48:49], v[38:39], v[48:49], v[50:51] neg_lo:[0,0,1] neg_hi:[0,0,1]
	v_lshlrev_b32_e32 v50, 16, v34
	v_and_b32_e32 v51, 0xffff0000, v34
	v_cvt_pk_bf16_f32 v80, v48, v49
	v_cvt_pk_bf16_f32 v76, v52, v53
	v_lshlrev_b32_e32 v48, 16, v30
	v_and_b32_e32 v49, 0xffff0000, v30
	v_pk_mul_f32 v[52:53], v[38:39], v[50:51]
	v_lshlrev_b32_e32 v26, 16, v27
	v_pk_fma_f32 v[52:53], v[42:43], v[48:49], v[52:53]
	v_pk_mul_f32 v[42:43], v[42:43], v[50:51]
	v_and_b32_e32 v27, 0xffff0000, v27
	v_pk_fma_f32 v[38:39], v[38:39], v[48:49], v[42:43] neg_lo:[0,0,1] neg_hi:[0,0,1]
	v_lshlrev_b32_e32 v22, 16, v23
	v_pk_mul_f32 v[48:49], v[38:39], s[16:17] op_sel_hi:[1,0]
	v_and_b32_e32 v23, 0xffff0000, v23
	v_pk_mul_f32 v[38:39], v[40:41], v[26:27]
	v_pk_mul_f32 v[26:27], v[44:45], v[26:27]
	v_pk_fma_f32 v[38:39], v[44:45], v[22:23], v[38:39]
	v_pk_fma_f32 v[22:23], v[40:41], v[22:23], v[26:27] neg_lo:[0,0,1] neg_hi:[0,0,1]
	v_lshlrev_b32_e32 v26, 16, v35
	v_and_b32_e32 v27, 0xffff0000, v35
	v_cvt_pk_bf16_f32 v81, v22, v23
	v_lshlrev_b32_e32 v22, 16, v31
	v_and_b32_e32 v23, 0xffff0000, v31
	v_pk_mul_f32 v[30:31], v[40:41], v[26:27]
	v_pk_mul_f32 v[26:27], v[44:45], v[26:27]
	v_cvt_pk_bf16_f32 v77, v38, v39
	v_pk_fma_f32 v[30:31], v[44:45], v[22:23], v[30:31]
	v_pk_fma_f32 v[22:23], v[40:41], v[22:23], v[26:27] neg_lo:[0,0,1] neg_hi:[0,0,1]
	v_mov_b64_e32 v[38:39], v[174:175]
	v_mov_b64_e32 v[40:41], v[176:177]
	v_mov_b64_e32 v[42:43], v[178:179]
	v_mov_b64_e32 v[44:45], v[180:181]
	v_lshlrev_b32_e32 v26, 16, v28
	v_and_b32_e32 v27, 0xffff0000, v28
	v_lshlrev_b32_e32 v10, 16, v24
	v_and_b32_e32 v11, 0xffff0000, v24
	v_lshlrev_b32_e32 v24, 16, v25
	v_and_b32_e32 v25, 0xffff0000, v25
	v_pk_mul_f32 v[30:31], v[30:31], s[16:17] op_sel_hi:[1,0]
	v_pk_mul_f32 v[22:23], v[22:23], s[16:17] op_sel_hi:[1,0]
	v_pk_mul_f32 v[52:53], v[52:53], s[16:17] op_sel_hi:[1,0]
	s_waitcnt vmcnt(0) lgkmcnt(0)
	v_pk_mul_f32 v[34:35], v[38:39], v[26:27]
	v_pk_mul_f32 v[26:27], v[42:43], v[26:27]
	v_pk_fma_f32 v[34:35], v[42:43], v[10:11], v[34:35]
	v_pk_fma_f32 v[10:11], v[38:39], v[10:11], v[26:27] neg_lo:[0,0,1] neg_hi:[0,0,1]
	v_lshlrev_b32_e32 v26, 16, v36
	v_and_b32_e32 v27, 0xffff0000, v36
	v_cvt_pk_bf16_f32 v82, v10, v11
	v_cvt_pk_bf16_f32 v78, v34, v35
	v_lshlrev_b32_e32 v10, 16, v32
	v_and_b32_e32 v11, 0xffff0000, v32
	v_pk_mul_f32 v[34:35], v[38:39], v[26:27]
	v_pk_mul_f32 v[26:27], v[42:43], v[26:27]
	v_pk_fma_f32 v[34:35], v[42:43], v[10:11], v[34:35]
	v_pk_fma_f32 v[10:11], v[38:39], v[10:11], v[26:27] neg_lo:[0,0,1] neg_hi:[0,0,1]
	v_lshlrev_b32_e32 v26, 16, v29
	v_pk_mul_f32 v[10:11], v[10:11], s[16:17] op_sel_hi:[1,0]
	v_and_b32_e32 v27, 0xffff0000, v29
	v_cvt_pk_bf16_f32 v46, v10, v11
	v_lshlrev_b32_e32 v10, 5, v2
	v_pk_mul_f32 v[28:29], v[40:41], v[26:27]
	v_pk_mul_f32 v[26:27], v[44:45], v[26:27]
	v_ashrrev_i32_e32 v11, 31, v10
	v_pk_fma_f32 v[28:29], v[44:45], v[24:25], v[28:29]
	v_pk_fma_f32 v[24:25], v[40:41], v[24:25], v[26:27] neg_lo:[0,0,1] neg_hi:[0,0,1]
	v_lshlrev_b32_e32 v26, 16, v37
	v_and_b32_e32 v27, 0xffff0000, v37
	v_lshlrev_b64 v[10:11], 2, v[10:11]
	v_or_b32_e32 v2, s34, v134
	v_cvt_pk_bf16_f32 v83, v24, v25
	v_cvt_pk_bf16_f32 v79, v28, v29
	v_lshlrev_b32_e32 v24, 16, v33
	v_and_b32_e32 v25, 0xffff0000, v33
	v_pk_mul_f32 v[28:29], v[40:41], v[26:27]
	v_pk_mul_f32 v[26:27], v[44:45], v[26:27]
	v_lshl_add_u64 v[38:39], v[4:5], 0, v[10:11]
	v_mad_i64_i32 v[4:5], s[38:39], v2, s72, v[8:9]
	v_pk_fma_f32 v[28:29], v[44:45], v[24:25], v[28:29]
	v_pk_fma_f32 v[24:25], v[40:41], v[24:25], v[26:27] neg_lo:[0,0,1] neg_hi:[0,0,1]
	v_lshl_add_u64 v[4:5], v[4:5], 0, s[40:41]
	v_pk_mul_f32 v[34:35], v[34:35], s[16:17] op_sel_hi:[1,0]
	v_pk_mul_f32 v[28:29], v[28:29], s[16:17] op_sel_hi:[1,0]
	v_pk_mul_f32 v[24:25], v[24:25], s[16:17] op_sel_hi:[1,0]
	v_lshl_add_u64 v[26:27], v[4:5], 0, v[20:21]
	v_cvt_pk_bf16_f32 v44, v48, v49
	v_cvt_pk_bf16_f32 v45, v22, v23
	v_cvt_pk_bf16_f32 v47, v24, v25
	v_cvt_pk_bf16_f32 v49, v30, v31
	v_cvt_pk_bf16_f32 v50, v34, v35
	v_cvt_pk_bf16_f32 v51, v28, v29
	v_lshl_add_u64 v[40:41], v[6:7], 0, v[10:11]
	global_load_dwordx4 v[4:7], v[26:27], off offset:2048
	global_load_dwordx4 v[8:11], v[26:27], off offset:2112
	global_load_dwordx4 v[22:25], v[26:27], off offset:2560
	s_nop 0
	global_load_dwordx4 v[26:29], v[26:27], off offset:2624
	s_nop 0
	global_load_dwordx4 v[30:33], v[38:39], off
	global_load_dwordx4 v[34:37], v[40:41], off
	global_load_dwordx4 v[174:177], v[38:39], off offset:16
	global_load_dwordx4 v[178:181], v[40:41], off offset:16
	v_cvt_pk_bf16_f32 v48, v52, v53
	v_sub_f32_e32 v2, v14, v18
	v_sub_f32_e32 v0, v0, v2
	v_add_f32_e32 v0, v16, v0
	v_add_f32_e32 v0, v0, v17
	v_add_f32_e32 v0, v12, v0
	v_cmp_nlt_f32_e64 s[38:39], 1.0, v102
	v_lshl_add_u64 v[12:13], s[20:21], 0, v[20:21]
	v_lshlrev_b32_e32 v2, 7, v133
	v_cndmask_b32_e64 v0, v205, v0, s[38:39]
	v_cmp_neq_f32_e64 s[38:39], 1.0, v102
	s_mov_b32 s20, 10
	s_waitcnt vmcnt(0) lgkmcnt(0)
; __device__ __forceinline__ void ld8bf(const bf16_t* p, float (&o)[8]) { unpack8(*(const u32x4*)p, o); }
; __device__ __forceinline__ bf16x8 pack_frag(const float (&v)[8]) { return __builtin_bit_cast(bf16x8, pack8(v)); }
; template <int KIND>
; __device__ __forceinline__ void w_m3_core(const bf16x8 (&Qf)[4][2], const bf16x8 (&Kf)[4][2], const bf16x8 (&Sf)[4][2], const LAS bf16_t* vT, float lg,
;                                           const bf16_t* gsrc, const float* nw, bf16_t* ydst, int lo, int fq) {
;     ...
;                     s = __builtin_amdgcn_mfma_f32_16x16x32_bf16(Kf[mb][0], Qf[nb][0], s, 0, 0, 0); s = __builtin_amdgcn_mfma_f32_16x16x32_bf16(Kf[mb][1], Qf[nb][1], s, 0, 0, 0);
; __device__ __forceinline__ void w_ret_m3(const Args& a, int l, unsigned char* ws, const bf16_t* proj, bf16_t* y, LAS unsigned char* wl, int b, int ck_, int h, int lane) {
;     ...
;         const bf16_t* ks = proj + (size_t)(row0 + n) * NIN + C_RK + 64 * h + 8 * fq;
;         ld8bf(ks, x1); ld8bf(ks + 32, x2);
; #pragma unroll
;         for (int j = 0; j < 8; ++j) { o1[j] = (x1[j] * cs[j] - x2[j] * sn[j]) * 0.125f; o2[j] = (x2[j] * cs[j] + x1[j] * sn[j]) * 0.125f; }
;         Kf[tb][0] = pack_frag(o1); Kf[tb][1] = pack_frag(o2);
;     }
;     const bf16_t* Sb = (const bf16_t*)((const unsigned char*)a.out + OUT_SBR) + (size_t)((b * NCH + ck_) * 4 + h) * 4096;
; #pragma unroll
;     for (int eb = 0; eb < 4; ++eb)
; #pragma unroll
;         for (int kk = 0; kk < 2; ++kk) Sf[eb][kk] = *(const bf16x8*)(Sb + (16 * eb + lo) * 64 + 32 * kk + 8 * fq);
	v_lshlrev_b32_e32 v42, 16, v4
	v_lshlrev_b32_e32 v52, 16, v8
	v_and_b32_e32 v53, 0xffff0000, v8
	v_and_b32_e32 v43, 0xffff0000, v4
	v_pk_mul_f32 v[54:55], v[30:31], v[52:53]
	v_pk_mul_f32 v[52:53], v[34:35], v[52:53]
	v_pk_fma_f32 v[54:55], v[34:35], v[42:43], v[54:55]
	v_pk_fma_f32 v[42:43], v[30:31], v[42:43], v[52:53] neg_lo:[0,0,1] neg_hi:[0,0,1]
	v_lshlrev_b32_e32 v52, 16, v26
	v_and_b32_e32 v53, 0xffff0000, v26
	v_cvt_pk_bf16_f32 v8, v42, v43
	v_cvt_pk_bf16_f32 v4, v54, v55
	v_lshlrev_b32_e32 v42, 16, v22
	v_and_b32_e32 v43, 0xffff0000, v22
	v_pk_mul_f32 v[54:55], v[30:31], v[52:53]
	v_lshlrev_b32_e32 v26, 16, v27
	v_pk_fma_f32 v[54:55], v[34:35], v[42:43], v[54:55]
	v_pk_mul_f32 v[34:35], v[34:35], v[52:53]
	v_and_b32_e32 v27, 0xffff0000, v27
	v_pk_fma_f32 v[30:31], v[30:31], v[42:43], v[34:35] neg_lo:[0,0,1] neg_hi:[0,0,1]
	v_lshlrev_b32_e32 v34, 16, v9
	v_and_b32_e32 v35, 0xffff0000, v9
	v_pk_mul_f32 v[42:43], v[30:31], s[16:17] op_sel_hi:[1,0]
	v_lshlrev_b32_e32 v30, 16, v5
	v_and_b32_e32 v31, 0xffff0000, v5
	v_pk_mul_f32 v[52:53], v[32:33], v[34:35]
	v_pk_mul_f32 v[34:35], v[36:37], v[34:35]
	v_pk_fma_f32 v[52:53], v[36:37], v[30:31], v[52:53]
	v_pk_fma_f32 v[30:31], v[32:33], v[30:31], v[34:35] neg_lo:[0,0,1] neg_hi:[0,0,1]
	v_lshlrev_b32_e32 v22, 16, v23
	v_cvt_pk_bf16_f32 v9, v30, v31
	v_and_b32_e32 v23, 0xffff0000, v23
	v_pk_mul_f32 v[30:31], v[32:33], v[26:27]
	v_pk_mul_f32 v[26:27], v[36:37], v[26:27]
	v_pk_fma_f32 v[30:31], v[36:37], v[22:23], v[30:31]
	v_pk_fma_f32 v[22:23], v[32:33], v[22:23], v[26:27] neg_lo:[0,0,1] neg_hi:[0,0,1]
	v_pk_mul_f32 v[58:59], v[30:31], s[16:17] op_sel_hi:[1,0]
	v_mov_b64_e32 v[30:31], v[174:175]
	v_mov_b64_e32 v[32:33], v[176:177]
	v_mov_b64_e32 v[34:35], v[178:179]
	v_mov_b64_e32 v[36:37], v[180:181]
	v_lshlrev_b32_e32 v38, 16, v10
	v_and_b32_e32 v39, 0xffff0000, v10
	v_lshlrev_b32_e32 v26, 16, v6
	v_and_b32_e32 v27, 0xffff0000, v6
	v_cndmask_b32_e64 v0, v206, v0, s[38:39]
	v_pk_mul_f32 v[56:57], v[54:55], s[16:17] op_sel_hi:[1,0]
	v_pk_mul_f32 v[22:23], v[22:23], s[16:17] op_sel_hi:[1,0]
	v_cvt_pk_bf16_f32 v5, v52, v53
	v_cvt_pk_bf16_f32 v52, v42, v43
	v_cvt_pk_bf16_f32 v53, v22, v23
	v_cvt_pk_bf16_f32 v56, v56, v57
	v_cvt_pk_bf16_f32 v57, v58, v59
	v_cndmask_b32_e64 v135, v0, -v102, vcc
	v_bfe_u32 v0, v101, 2, 2
	v_or_b32_e32 v105, v124, v0
	v_or_b32_e32 v106, v140, v0
	v_lshlrev_b32_e32 v0, 6, v100
	v_mfma_f32_16x16x32_bf16 v[100:103], v[64:67], v[96:99], 0
	v_cmp_lt_i32_e32 vcc, v133, v124
	v_mul_f32_e32 v1, v135, v1
	v_mul_f32_e32 v1, 0x3fb8aa3b, v1
	v_mfma_f32_16x16x32_bf16 v[100:103], v[72:75], v[92:95], v[100:103]
	v_exp_f32_e32 v1, v1
	s_waitcnt vmcnt(0) lgkmcnt(0)
	v_pk_mul_f32 v[40:41], v[30:31], v[38:39]
	v_pk_mul_f32 v[38:39], v[34:35], v[38:39]
	v_pk_fma_f32 v[40:41], v[34:35], v[26:27], v[40:41]
	v_pk_fma_f32 v[26:27], v[30:31], v[26:27], v[38:39] neg_lo:[0,0,1] neg_hi:[0,0,1]
	v_lshlrev_b32_e32 v38, 16, v28
	v_and_b32_e32 v39, 0xffff0000, v28
	v_cvt_pk_bf16_f32 v10, v26, v27
	v_cvt_pk_bf16_f32 v6, v40, v41
	v_lshlrev_b32_e32 v26, 16, v24
	v_and_b32_e32 v27, 0xffff0000, v24
	v_pk_mul_f32 v[40:41], v[30:31], v[38:39]
	v_lshlrev_b32_e32 v28, 16, v29
	v_pk_fma_f32 v[40:41], v[34:35], v[26:27], v[40:41]
	v_pk_mul_f32 v[34:35], v[34:35], v[38:39]
	v_and_b32_e32 v29, 0xffff0000, v29
	v_pk_fma_f32 v[26:27], v[30:31], v[26:27], v[34:35] neg_lo:[0,0,1] neg_hi:[0,0,1]
	v_lshlrev_b32_e32 v34, 16, v11
	v_and_b32_e32 v35, 0xffff0000, v11
	v_lshlrev_b32_e32 v30, 16, v7
	v_and_b32_e32 v31, 0xffff0000, v7
	v_pk_mul_f32 v[38:39], v[32:33], v[34:35]
	v_pk_mul_f32 v[34:35], v[36:37], v[34:35]
	v_pk_fma_f32 v[38:39], v[36:37], v[30:31], v[38:39]
	v_pk_fma_f32 v[30:31], v[32:33], v[30:31], v[34:35] neg_lo:[0,0,1] neg_hi:[0,0,1]
	v_lshlrev_b32_e32 v24, 16, v25
	v_cvt_pk_bf16_f32 v11, v30, v31
	v_and_b32_e32 v25, 0xffff0000, v25
	v_pk_mul_f32 v[30:31], v[32:33], v[28:29]
	v_pk_mul_f32 v[28:29], v[36:37], v[28:29]
	v_pk_fma_f32 v[30:31], v[36:37], v[24:25], v[30:31]
	v_pk_fma_f32 v[24:25], v[32:33], v[24:25], v[28:29] neg_lo:[0,0,1] neg_hi:[0,0,1]
	v_lshl_add_u64 v[28:29], v[12:13], 0, v[2:3]
	v_add_co_u32_e64 v32, s[38:39], s73, v28
	v_pk_mul_f32 v[40:41], v[40:41], s[16:17] op_sel_hi:[1,0]
	v_pk_mul_f32 v[26:27], v[26:27], s[16:17] op_sel_hi:[1,0]
	v_pk_mul_f32 v[30:31], v[30:31], s[16:17] op_sel_hi:[1,0]
	v_pk_mul_f32 v[24:25], v[24:25], s[16:17] op_sel_hi:[1,0]
	v_addc_co_u32_e64 v33, s[38:39], 0, v29, s[38:39]
	v_cvt_pk_bf16_f32 v7, v38, v39
	v_cvt_pk_bf16_f32 v54, v26, v27
	v_cvt_pk_bf16_f32 v55, v24, v25
	v_cvt_pk_bf16_f32 v58, v40, v41
	v_cvt_pk_bf16_f32 v59, v30, v31
	global_load_dwordx4 v[20:23], v[28:29], off
	global_load_dwordx4 v[12:15], v[28:29], off offset:64
	global_load_dwordx4 v[24:27], v[28:29], off offset:2048
	global_load_dwordx4 v[16:19], v[28:29], off offset:2112
	global_load_dwordx4 v[36:39], v[32:33], off
	s_nop 0
	global_load_dwordx4 v[28:31], v[32:33], off offset:64
	global_load_dwordx4 v[40:43], v[32:33], off offset:2048
	s_nop 0
	global_load_dwordx4 v[32:35], v[32:33], off offset:2112
	v_lshlrev_b32_e32 v2, 2, v133
	v_bitop3_b32 v138, v0, 64, v2 bitop3:0x36
	v_bitop3_b32 v137, v0, s96, v2 bitop3:0x36
	v_sub_u32_e32 v0, v133, v124
	v_cvt_f32_i32_e32 v0, v0
	s_waitcnt lgkmcnt(0)
	s_ashr_i32 s21, s20, 31
	v_mul_f32_e32 v0, v135, v0
	v_mul_f32_e32 v0, 0x3fb8aa3b, v0
	v_exp_f32_e32 v139, v0
	s_lshl_b64 s[20:21], s[20:21], 3
	s_add_u32 s20, s0, s20
	s_addc_u32 s21, s1, s21
	v_mul_f32_e32 v0, v139, v100
	v_cndmask_b32_e64 v2, v0, 0, vcc
	v_add_u32_e32 v0, v133, v143
	v_cvt_f32_i32_e32 v0, v0
	s_load_dwordx2 s[20:21], s[20:21], 0x0
	s_lshl_b64 s[38:39], s[36:37], 2
	s_waitcnt vmcnt(7)
; template <int KIND>
; __device__ __forceinline__ void w_m3_core(const bf16x8 (&Qf)[4][2], const bf16x8 (&Kf)[4][2], const bf16x8 (&Sf)[4][2], const LAS bf16_t* vT, float lg,
;                                           const bf16_t* gsrc, const float* nw, bf16_t* ydst, int lo, int fq) {
;     ...
;             float pv[8];
; #pragma unroll
;             for (int hh = 0; hh < 2; ++hh) { const int mb = 2 * kk2 + hh;
;                 if (mb <= nb) { f32x4 s = {0.f, 0.f, 0.f, 0.f};
;                     s = __builtin_amdgcn_mfma_f32_16x16x32_bf16(Kf[mb][0], Qf[nb][0], s, 0, 0, 0); s = __builtin_amdgcn_mfma_f32_16x16x32_bf16(Kf[mb][1], Qf[nb][1], s, 0, 0, 0);
; #pragma unroll
;                     for (int r = 0; r < 4; ++r) { const int m = 16 * mb + 4 * fq + r, n = 16 * nb + lo; float v = s[r];
;                         if (KIND == 0) v *= __expf((float)(n - m) * lg);
;                         if (mb == nb) v = (m <= n) ? v : 0.f;
;                         pv[4 * hh + r] = v; }
;                 } else {
; #pragma unroll
;                     for (int r = 0; r < 4; ++r) pv[4 * hh + r] = 0.f; }
;             }
;             const bf16x8 Pf = pack_frag(pv);
; #pragma unroll
;             for (int eb = 0; eb < 4; ++eb)
;                 O[eb] = __builtin_amdgcn_mfma_f32_16x16x32_bf16(tr_frag(vT, 32 * kk2 + 4 * fq, 32 * kk2 + 16 + 4 * fq, 16 * eb, lo), Pf, O[eb], 0, 0, 0);
;         }
; #pragma unroll
;         for (int kk = 0; kk < 2; ++kk)
; #pragma unroll
;             for (int eb = 0; eb < 4; ++eb) O2[eb] = __builtin_amdgcn_mfma_f32_16x16x32_bf16(Sf[eb][kk], Qf[nb][kk], O2[eb], 0, 0, 0);
;         const float osc = KIND == 0 ? __expf((float)(16 * nb + lo + 1) * lg) : 1.0f;
; #pragma unroll
;         for (int eb = 0; eb < 4; ++eb) O[eb] = O[eb] + O2[eb] * osc;
;         float ss = 0.f;
; #pragma unroll
;         for (int eb = 0; eb < 4; ++eb) ss += (O[eb][0] * O[eb][0] + O[eb][1] * O[eb][1]) + (O[eb][2] * O[eb][2] + O[eb][3] * O[eb][3]);
;         { const int ln = (fq << 4) | lo; ss += bperm_f(ln ^ 16, ss); ss += bperm_f(ln ^ 32, ss); }
;         const float rs = rsqrtf(ss * (1.0f / 64.0f) + EPS);
;         const size_t n = 16 * nb + lo;
; #pragma unroll
;         for (int eb = 0; eb < 4; ++eb) { const int e0 = 16 * eb + 4 * fq;
;             const unsigned long long gw_ = *(const unsigned long long*)(gsrc + n * NIN + e0); const f32x4 w4 = *(const f32x4*)(nw + e0);
	v_mfma_f32_16x16x32_bf16 v[116:119], v[20:23], v[96:99], 0
	v_mul_f32_e32 v0, v135, v0
	v_mul_f32_e32 v0, 0x3fb8aa3b, v0
	v_exp_f32_e32 v0, v0
	s_waitcnt lgkmcnt(0)
	s_add_u32 s27, s20, s38
	s_addc_u32 s38, s21, s39
	s_lshl_b64 s[20:21], s[24:25], 2
	s_add_u32 s44, s27, s20
	s_addc_u32 s45, s38, s21
	v_lshl_add_u64 v[182:183], v[124:125], 2, s[44:45]
	global_load_dwordx4 v[184:187], v[182:183], off
	global_load_dwordx4 v[188:191], v[182:183], off offset:64
	global_load_dwordx4 v[192:195], v[182:183], off offset:128
	global_load_dwordx4 v[196:199], v[182:183], off offset:192
	v_mul_f32_e32 v0, v0, v101
	v_cmp_gt_i32_e64 s[38:39], v133, v124
	s_lshl_b64 s[20:21], s[34:35], 11
	s_add_u32 s20, s10, s20
	v_cndmask_b32_e64 v107, 0, v0, s[38:39]
	v_sub_u32_e32 v0, v133, v142
	v_cvt_f32_i32_e32 v0, v0
	s_addc_u32 s21, s11, s21
	s_add_u32 s40, s20, s40
	s_addc_u32 s41, s21, 0
	v_mul_f32_e32 v0, v135, v0
	v_mul_f32_e32 v0, 0x3fb8aa3b, v0
	v_exp_f32_e32 v0, v0
	v_mad_u64_u32 v[126:127], s[20:21], v106, s23, v[104:105]
	v_mad_u64_u32 v[128:129], s[20:21], v105, s23, v[104:105]
	v_pk_mul_f32 v[100:101], v[0:1], v[102:103]
	v_cmp_ge_i32_e64 s[38:39], v133, v142
	v_cvt_pk_bf16_f32 v1, v100, v101
	ds_read_b64_tr_b16 v[102:103], v126
	ds_read_b64_tr_b16 v[110:111], v126 offset:32
	ds_read_b64_tr_b16 v[100:101], v128
	ds_read_b64_tr_b16 v[108:109], v128 offset:32
	v_cvt_pk_bf16_f32 v0, v2, v107
	v_cndmask_b32_e64 v2, 0, v1, s[38:39]
	v_lshrrev_b32_e32 v1, 16, v1
	v_cmp_ge_i32_e64 s[38:39], v133, v141
	s_waitcnt vmcnt(9)
	v_mfma_f32_16x16x32_bf16 v[146:149], v[24:27], v[96:99], 0
	v_cndmask_b32_e64 v1, 0, v1, s[38:39]
	v_perm_b32 v1, v1, v2, s53
	v_mov_b32_e32 v2, v3
	s_waitcnt vmcnt(7)
	v_mfma_f32_16x16x32_bf16 v[150:153], v[36:39], v[96:99], 0
	s_waitcnt lgkmcnt(1)
	v_mfma_f32_16x16x32_bf16 v[104:107], v[100:103], v[0:3], 0
	s_waitcnt lgkmcnt(0)
	v_mfma_f32_16x16x32_bf16 v[100:103], v[108:111], v[0:3], 0
	ds_read_b64_tr_b16 v[108:109], v128 offset:64
	ds_read_b64_tr_b16 v[110:111], v126 offset:64
	ds_read_b64_tr_b16 v[112:113], v128 offset:96
	ds_read_b64_tr_b16 v[114:115], v126 offset:96
	s_waitcnt lgkmcnt(2)
	v_mfma_f32_16x16x32_bf16 v[108:111], v[108:111], v[0:3], 0
	s_waitcnt lgkmcnt(0)
	v_mfma_f32_16x16x32_bf16 v[112:115], v[112:115], v[0:3], 0
	v_add_u32_e32 v0, 1, v133
	v_cvt_f32_ubyte0_e32 v0, v0
	v_mul_f32_e32 v0, v135, v0
	s_waitcnt vmcnt(5)
	v_mfma_f32_16x16x32_bf16 v[154:157], v[40:43], v[96:99], 0
	v_mul_f32_e32 v0, 0x3fb8aa3b, v0
	v_exp_f32_e32 v2, v0
	v_mfma_f32_16x16x32_bf16 v[120:123], v[12:15], v[92:95], v[116:119]
	v_mfma_f32_16x16x32_bf16 v[116:119], v[16:19], v[92:95], v[146:149]
	v_mfma_f32_16x16x32_bf16 v[96:99], v[28:31], v[92:95], v[150:153]
	s_nop 5
	v_fma_f32 v122, v2, v122, v106
	v_fma_f32 v123, v2, v123, v107
	v_pk_fma_f32 v[120:121], v[2:3], v[120:121], v[104:105] op_sel_hi:[0,1,1]
	v_pk_fma_f32 v[118:119], v[2:3], v[118:119], v[102:103] op_sel_hi:[0,1,1]
	s_waitcnt vmcnt(4)
	v_mfma_f32_16x16x32_bf16 v[92:95], v[32:35], v[92:95], v[154:157]
	v_fma_f32 v116, v2, v116, v100
	v_fma_f32 v117, v2, v117, v101
	v_pk_fma_f32 v[108:109], v[2:3], v[96:97], v[108:109] op_sel_hi:[0,1,1]
	v_pk_fma_f32 v[106:107], v[2:3], v[98:99], v[110:111] op_sel_hi:[0,1,1]
	v_lshl_add_u64 v[100:101], v[124:125], 2, s[44:45]
	s_nop 2
	v_pk_fma_f32 v[0:1], v[2:3], v[94:95], v[114:115] op_sel_hi:[0,1,1]
	v_pk_fma_f32 v[104:105], v[2:3], v[92:93], v[112:113] op_sel_hi:[0,1,1]
	v_pk_mul_f32 v[92:93], v[122:123], v[122:123]
	v_pk_mul_f32 v[94:95], v[120:121], v[120:121]
	v_mul_f32_e32 v2, v104, v104
	v_pk_mov_b32 v[96:97], v[94:95], v[92:93] op_sel:[1,0]
	v_mov_b32_e32 v95, v93
	v_pk_add_f32 v[92:93], v[96:97], v[94:95]
	v_pk_mul_f32 v[94:95], v[118:119], v[118:119]
	v_pk_mul_f32 v[96:97], v[116:117], v[116:117]
	v_pk_add_f32 v[92:93], v[92:93], v[92:93] op_sel:[0,1] op_sel_hi:[1,0]
	v_pk_mov_b32 v[98:99], v[96:97], v[94:95] op_sel:[1,0]
	v_mov_b32_e32 v97, v95
	v_pk_add_f32 v[94:95], v[98:99], v[96:97]
	v_mul_f32_e32 v96, v105, v105
	v_pk_add_f32 v[94:95], v[94:95], v[94:95] op_sel:[0,1] op_sel_hi:[1,0]
	v_mov_b32_e32 v93, v2
	v_mov_b32_e32 v95, v96
	v_mul_f32_e32 v2, v109, v109
	v_mul_f32_e32 v97, v0, v0
	v_pk_add_f32 v[92:93], v[92:93], v[94:95]
	v_pk_fma_f32 v[94:95], v[108:109], v[108:109], v[2:3] op_sel_hi:[1,1,0]
	v_mul_f32_e32 v2, v107, v107
	v_mul_f32_e32 v98, v1, v1
	v_mov_b32_e32 v95, v97
	v_pk_fma_f32 v[96:97], v[106:107], v[106:107], v[2:3] op_sel_hi:[1,1,0]
	s_nop 0
	v_mov_b32_e32 v97, v98
	v_pk_add_f32 v[94:95], v[94:95], v[96:97]
	v_mov_b64_e32 v[98:99], s[42:43]
	v_pk_add_f32 v[92:93], v[92:93], v[94:95]
	v_lshlrev_b64 v[96:97], 1, v[124:125]
	v_add_f32_e32 v2, v92, v93
	ds_bpermute_b32 v92, v138, v2
	s_waitcnt lgkmcnt(0)
	v_add_f32_e32 v2, v2, v92
	ds_bpermute_b32 v92, v137, v2
	s_waitcnt lgkmcnt(0)
	v_add_f32_e32 v2, v2, v92
	v_fmamk_f32 v2, v2, 0x3c800000, v200
	v_cmp_gt_f32_e64 s[38:39], s29, v2
	v_mul_f32_e32 v92, 0x4b800000, v2
	s_nop 0
	v_cndmask_b32_e64 v2, v2, v92, s[38:39]
	v_rsq_f32_e32 v2, v2
	s_nop 0
	v_mul_f32_e32 v92, 0x45800000, v2
	v_cndmask_b32_e64 v102, v2, v92, s[38:39]
	v_mad_u64_u32 v[92:93], s[20:21], v133, s72, v[98:99]
	v_lshl_add_u64 v[110:111], v[92:93], 0, v[96:97]
	s_waitcnt vmcnt(0)
	v_mov_b64_e32 v[114:115], v[222:223]
	v_mov_b64_e32 v[92:93], v[184:185]
	v_mov_b64_e32 v[94:95], v[186:187]
	v_lshlrev_b32_e32 v2, 11, v133
	v_lshl_add_u64 v[112:113], s[40:41], 0, v[2:3]
	v_pk_mul_f32 v[120:121], v[120:121], v[102:103] op_sel_hi:[1,0]
	v_pk_mul_f32 v[122:123], v[122:123], v[102:103] op_sel_hi:[1,0]
	v_lshl_add_u64 v[112:113], v[112:113], 0, v[96:97]
	v_pk_mul_f32 v[116:117], v[116:117], v[102:103] op_sel_hi:[1,0]
	v_pk_mul_f32 v[118:119], v[118:119], v[102:103] op_sel_hi:[1,0]
	v_pk_mul_f32 v[108:109], v[108:109], v[102:103] op_sel_hi:[1,0]
	s_waitcnt lgkmcnt(0)
; __device__ __forceinline__ unsigned pk2(float lo, float hi) { const f32x2_t v = {lo, hi}; const bf16x2_t b = __builtin_convertvector(v, bf16x2_t); return __builtin_bit_cast(unsigned, b); }
; __device__ __forceinline__ float sigmoidf_(float x) { return __builtin_amdgcn_rcpf(1.0f + __expf(-x)); }
; template <int KIND>
; __device__ __forceinline__ void w_m3_core(const bf16x8 (&Qf)[4][2], const bf16x8 (&Kf)[4][2], const bf16x8 (&Sf)[4][2], const LAS bf16_t* vT, float lg,
;                                           const bf16_t* gsrc, const float* nw, bf16_t* ydst, int lo, int fq) {
;     ...
;                     s = __builtin_amdgcn_mfma_f32_16x16x32_bf16(Kf[mb][0], Qf[nb][0], s, 0, 0, 0); s = __builtin_amdgcn_mfma_f32_16x16x32_bf16(Kf[mb][1], Qf[nb][1], s, 0, 0, 0);
; #pragma unroll
;                     for (int r = 0; r < 4; ++r) { const int m = 16 * mb + 4 * fq + r, n = 16 * nb + lo; float v = s[r];
;                         if (KIND == 0) v *= __expf((float)(n - m) * lg);
;                         if (mb == nb) v = (m <= n) ? v : 0.f;
;                         pv[4 * hh + r] = v; }
;     ...
;         const size_t n = 16 * nb + lo;
; #pragma unroll
;         for (int eb = 0; eb < 4; ++eb) { const int e0 = 16 * eb + 4 * fq;
;             const unsigned long long gw_ = *(const unsigned long long*)(gsrc + n * NIN + e0); const f32x4 w4 = *(const f32x4*)(nw + e0);
;             const float g0 = __uint_as_float((unsigned)gw_ << 16), g1 = __uint_as_float((unsigned)gw_ & 0xffff0000u), g2 = __uint_as_float((unsigned)(gw_ >> 32) << 16), g3 = __uint_as_float((unsigned)(gw_ >> 32) & 0xffff0000u);
;             const float o0 = O[eb][0] * rs * w4[0] * (g0 * sigmoidf_(g0)), o1 = O[eb][1] * rs * w4[1] * (g1 * sigmoidf_(g1));
;             const float o2 = O[eb][2] * rs * w4[2] * (g2 * sigmoidf_(g2)), o3 = O[eb][3] * rs * w4[3] * (g3 * sigmoidf_(g3));
;             *(unsigned long long*)(ydst + n * DM + e0) = (unsigned long long)pk2(o0, o1) | ((unsigned long long)pk2(o2, o3) << 32); }
	v_lshlrev_b32_e32 v130, 16, v114
	v_mul_f32_e32 v2, 0xbfb8aa3b, v130
	v_exp_f32_e32 v2, v2
	v_and_b32_e32 v131, 0xffff0000, v114
	v_lshlrev_b32_e32 v114, 16, v115
	v_and_b32_e32 v115, 0xffff0000, v115
	v_add_f32_e32 v2, 1.0, v2
	v_rcp_f32_e32 v146, v2
	v_mul_f32_e32 v2, 0xbfb8aa3b, v131
	v_exp_f32_e32 v2, v2
	v_pk_mul_f32 v[92:93], v[92:93], v[120:121]
	v_pk_mul_f32 v[94:95], v[94:95], v[122:123]
	v_add_f32_e32 v2, 1.0, v2
	v_rcp_f32_e32 v147, v2
	v_mul_f32_e32 v2, 0xbfb8aa3b, v114
	v_exp_f32_e32 v2, v2
	v_pk_mul_f32 v[120:121], v[146:147], v[130:131]
	s_nop 0
	v_pk_mul_f32 v[92:93], v[120:121], v[92:93]
	v_add_f32_e32 v2, 1.0, v2
	v_rcp_f32_e32 v120, v2
	v_mul_f32_e32 v2, 0xbfb8aa3b, v115
	v_exp_f32_e32 v2, v2
	v_cvt_pk_bf16_f32 v92, v92, v93
	v_add_f32_e32 v2, 1.0, v2
	v_rcp_f32_e32 v121, v2
	s_nop 0
	v_pk_mul_f32 v[114:115], v[120:121], v[114:115]
	s_nop 0
	v_pk_mul_f32 v[94:95], v[114:115], v[94:95]
	s_nop 0
	v_cvt_pk_bf16_f32 v93, v94, v95
	global_store_dwordx2 v[112:113], v[92:93], off offset:1024
	v_mov_b64_e32 v[114:115], v[224:225]
	s_nop 0
	v_mov_b64_e32 v[92:93], v[188:189]
	v_mov_b64_e32 v[94:95], v[190:191]
	s_waitcnt lgkmcnt(0)
	v_lshlrev_b32_e32 v120, 16, v114
	v_mul_f32_e32 v2, 0xbfb8aa3b, v120
	v_exp_f32_e32 v2, v2
	v_and_b32_e32 v121, 0xffff0000, v114
	v_lshlrev_b32_e32 v114, 16, v115
	v_and_b32_e32 v115, 0xffff0000, v115
	v_add_f32_e32 v2, 1.0, v2
	v_rcp_f32_e32 v122, v2
	v_mul_f32_e32 v2, 0xbfb8aa3b, v121
	v_exp_f32_e32 v2, v2
	v_pk_mul_f32 v[92:93], v[92:93], v[116:117]
	v_pk_mul_f32 v[94:95], v[94:95], v[118:119]
	v_add_f32_e32 v2, 1.0, v2
	v_rcp_f32_e32 v123, v2
	v_mul_f32_e32 v2, 0xbfb8aa3b, v114
	v_exp_f32_e32 v2, v2
	v_pk_mul_f32 v[116:117], v[122:123], v[120:121]
	s_nop 0
	v_pk_mul_f32 v[92:93], v[116:117], v[92:93]
	v_add_f32_e32 v2, 1.0, v2
	v_rcp_f32_e32 v116, v2
	v_mul_f32_e32 v2, 0xbfb8aa3b, v115
	v_exp_f32_e32 v2, v2
	v_cvt_pk_bf16_f32 v92, v92, v93
	v_add_f32_e32 v2, 1.0, v2
	v_rcp_f32_e32 v117, v2
	s_nop 0
	v_pk_mul_f32 v[114:115], v[116:117], v[114:115]
	s_nop 0
	v_pk_mul_f32 v[94:95], v[114:115], v[94:95]
	v_mul_f32_e32 v116, v106, v102
	v_cvt_pk_bf16_f32 v93, v94, v95
	global_store_dwordx2 v[112:113], v[92:93], off offset:1056
	v_mov_b64_e32 v[114:115], v[226:227]
	s_nop 0
	v_mov_b64_e32 v[92:93], v[192:193]
	v_mov_b64_e32 v[94:95], v[194:195]
	s_waitcnt lgkmcnt(0)
	v_lshlrev_b32_e32 v118, 16, v114
	v_mul_f32_e32 v2, 0xbfb8aa3b, v118
	v_exp_f32_e32 v2, v2
	v_and_b32_e32 v119, 0xffff0000, v114
	v_lshlrev_b32_e32 v117, 16, v115
	v_and_b32_e32 v115, 0xffff0000, v115
	v_add_f32_e32 v2, 1.0, v2
	v_rcp_f32_e32 v120, v2
	v_mul_f32_e32 v2, 0xbfb8aa3b, v119
	v_exp_f32_e32 v2, v2
	v_pk_mul_f32 v[92:93], v[92:93], v[108:109]
	v_mul_f32_e32 v114, v107, v102
	v_mov_b32_e32 v106, v95
	v_add_f32_e32 v2, 1.0, v2
	v_rcp_f32_e32 v121, v2
	v_mul_f32_e32 v2, 0xbfb8aa3b, v117
	v_exp_f32_e32 v2, v2
	v_pk_mul_f32 v[108:109], v[120:121], v[118:119]
	s_nop 0
	v_pk_mul_f32 v[92:93], v[108:109], v[92:93]
	v_add_f32_e32 v2, 1.0, v2
	v_rcp_f32_e32 v109, v2
	v_mul_f32_e32 v2, 0xbfb8aa3b, v115
	v_exp_f32_e32 v2, v2
	v_mov_b32_e32 v108, v94
	v_pk_mul_f32 v[108:109], v[108:109], v[116:117]
	v_cvt_pk_bf16_f32 v92, v92, v93
	v_add_f32_e32 v2, 1.0, v2
	v_rcp_f32_e32 v107, v2
	s_nop 0
	v_pk_mul_f32 v[94:95], v[106:107], v[114:115]
	v_mov_b32_e32 v106, v108
	v_mov_b32_e32 v107, v94
	v_mov_b32_e32 v94, v109
	v_pk_mul_f32 v[94:95], v[106:107], v[94:95]
	v_mul_f32_e32 v106, v0, v102
	v_cvt_pk_bf16_f32 v93, v94, v95
	global_store_dwordx2 v[112:113], v[92:93], off offset:1088
	v_mov_b64_e32 v[114:115], v[228:229]
	s_nop 0
	v_mov_b64_e32 v[92:93], v[196:197]
	v_mov_b64_e32 v[94:95], v[198:199]
	v_mul_f32_e32 v108, v105, v102
	v_mul_f32_e32 v110, v104, v102
	v_mul_f32_e32 v102, v1, v102
	s_waitcnt lgkmcnt(0)
	v_lshlrev_b32_e32 v111, 16, v114
	v_mul_f32_e32 v2, 0xbfb8aa3b, v111
	v_exp_f32_e32 v2, v2
	v_and_b32_e32 v109, 0xffff0000, v114
	v_lshlrev_b32_e32 v107, 16, v115
	v_and_b32_e32 v103, 0xffff0000, v115
	v_add_f32_e32 v2, 1.0, v2
	v_rcp_f32_e32 v115, v2
	v_mul_f32_e32 v2, 0xbfb8aa3b, v109
	v_exp_f32_e32 v2, v2
	v_mul_f32_e32 v0, 0xbfb8aa3b, v107
	v_exp_f32_e32 v0, v0
	v_mov_b32_e32 v104, v93
	v_add_f32_e32 v2, 1.0, v2
	v_rcp_f32_e32 v105, v2
	v_add_f32_e32 v0, 1.0, v0
	v_mov_b32_e32 v114, v92
	v_pk_mul_f32 v[110:111], v[114:115], v[110:111]
	v_pk_mul_f32 v[92:93], v[104:105], v[108:109]
	v_rcp_f32_e32 v105, v0
	v_mul_f32_e32 v0, 0xbfb8aa3b, v103
	v_exp_f32_e32 v0, v0
	v_mov_b32_e32 v104, v94
	v_pk_mul_f32 v[104:105], v[104:105], v[106:107]
	v_mov_b32_e32 v94, v110
	v_add_f32_e32 v0, 1.0, v0
	v_rcp_f32_e32 v1, v0
	v_mov_b32_e32 v0, v95
	v_mov_b32_e32 v95, v92
	v_mov_b32_e32 v92, v111
	v_pk_mul_f32 v[0:1], v[0:1], v[102:103]
	v_pk_mul_f32 v[92:93], v[94:95], v[92:93]
	v_mov_b32_e32 v94, v104
	v_mov_b32_e32 v95, v0
	v_mov_b32_e32 v0, v105
	v_pk_mul_f32 v[0:1], v[94:95], v[0:1]
	v_cvt_pk_bf16_f32 v92, v92, v93
	v_cvt_pk_bf16_f32 v93, v0, v1
	global_store_dwordx2 v[112:113], v[92:93], off offset:1120
	v_sub_u32_e32 v0, v144, v124
	v_add_u32_e32 v1, v144, v143
	v_cvt_f32_i32_e32 v0, v0
	v_cvt_f32_i32_e32 v1, v1
	v_mfma_f32_16x16x32_bf16 v[92:95], v[64:67], v[88:91], 0
	v_sub_u32_e32 v2, v144, v142
	v_mul_f32_e32 v0, v135, v0
	v_mul_f32_e32 v1, v135, v1
	v_cvt_f32_i32_e32 v2, v2
	v_mul_f32_e32 v0, 0x3fb8aa3b, v0
	v_mul_f32_e32 v1, 0x3fb8aa3b, v1
	v_mfma_f32_16x16x32_bf16 v[92:95], v[72:75], v[84:87], v[92:95]
	v_exp_f32_e32 v0, v0
	v_exp_f32_e32 v1, v1
	v_mul_f32_e32 v2, v135, v2
	v_mul_f32_e32 v2, 0x3fb8aa3b, v2
	v_add_u32_e32 v115, 17, v124
	s_nop 2
	v_pk_mul_f32 v[0:1], v[0:1], v[92:93]
	v_exp_f32_e32 v92, v2
	v_sub_u32_e32 v2, v144, v141
; template <int KIND>
; __device__ __forceinline__ void w_m3_core(const bf16x8 (&Qf)[4][2], const bf16x8 (&Kf)[4][2], const bf16x8 (&Sf)[4][2], const LAS bf16_t* vT, float lg,
;                                           const bf16_t* gsrc, const float* nw, bf16_t* ydst, int lo, int fq) {
;     ...
;             float pv[8];
; #pragma unroll
;             for (int hh = 0; hh < 2; ++hh) { const int mb = 2 * kk2 + hh;
;                 if (mb <= nb) { f32x4 s = {0.f, 0.f, 0.f, 0.f};
;                     s = __builtin_amdgcn_mfma_f32_16x16x32_bf16(Kf[mb][0], Qf[nb][0], s, 0, 0, 0); s = __builtin_amdgcn_mfma_f32_16x16x32_bf16(Kf[mb][1], Qf[nb][1], s, 0, 0, 0);
; #pragma unroll
;                     for (int r = 0; r < 4; ++r) { const int m = 16 * mb + 4 * fq + r, n = 16 * nb + lo; float v = s[r];
;                         if (KIND == 0) v *= __expf((float)(n - m) * lg);
;                         if (mb == nb) v = (m <= n) ? v : 0.f;
;                         pv[4 * hh + r] = v; }
;                 } else {
; #pragma unroll
;                     for (int r = 0; r < 4; ++r) pv[4 * hh + r] = 0.f; }
;             }
;             const bf16x8 Pf = pack_frag(pv);
; #pragma unroll
;             for (int eb = 0; eb < 4; ++eb)
;                 O[eb] = __builtin_amdgcn_mfma_f32_16x16x32_bf16(tr_frag(vT, 32 * kk2 + 4 * fq, 32 * kk2 + 16 + 4 * fq, 16 * eb, lo), Pf, O[eb], 0, 0, 0);
;         }
; #pragma unroll
;         for (int kk = 0; kk < 2; ++kk)
; #pragma unroll
;             for (int eb = 0; eb < 4; ++eb) O2[eb] = __builtin_amdgcn_mfma_f32_16x16x32_bf16(Sf[eb][kk], Qf[nb][kk], O2[eb], 0, 0, 0);
;         const float osc = KIND == 0 ? __expf((float)(16 * nb + lo + 1) * lg) : 1.0f;
; #pragma unroll
;         for (int eb = 0; eb < 4; ++eb) O[eb] = O[eb] + O2[eb] * osc;
;         float ss = 0.f;
; #pragma unroll
;         for (int eb = 0; eb < 4; ++eb) ss += (O[eb][0] * O[eb][0] + O[eb][1] * O[eb][1]) + (O[eb][2] * O[eb][2] + O[eb][3] * O[eb][3]);
;         { const int ln = (fq << 4) | lo; ss += bperm_f(ln ^ 16, ss); ss += bperm_f(ln ^ 32, ss); }
;         const float rs = rsqrtf(ss * (1.0f / 64.0f) + EPS);
;         const size_t n = 16 * nb + lo;
; #pragma unroll
;         for (int eb = 0; eb < 4; ++eb) { const int e0 = 16 * eb + 4 * fq;
;             const unsigned long long gw_ = *(const unsigned long long*)(gsrc + n * NIN + e0); const f32x4 w4 = *(const f32x4*)(nw + e0);
	v_cvt_f32_i32_e32 v2, v2
	v_cmp_ge_i32_e64 s[38:39], v144, v115
	v_add_u32_e32 v114, 19, v124
	v_add_u32_e32 v116, 18, v124
	v_mul_f32_e32 v2, v135, v2
	v_mul_f32_e32 v2, 0x3fb8aa3b, v2
	v_exp_f32_e32 v93, v2
	v_mfma_f32_16x16x32_bf16 v[110:113], v[36:39], v[88:91], 0
	v_mul_f32_e64 v102, v92, v94
	v_mul_f32_e64 v103, v93, v95
	v_mfma_f32_16x16x32_bf16 v[92:95], v[60:63], v[88:91], 0
	v_mfma_f32_16x16x32_bf16 v[92:95], v[68:71], v[84:87], v[92:95]
	v_mfma_f32_16x16x32_bf16 v[158:161], v[28:31], v[84:87], v[110:113]
	s_nop 6
	v_mul_f32_e32 v2, v139, v92
	v_sub_u32_e32 v92, v144, v115
	v_cvt_f32_i32_e32 v92, v92
	v_cndmask_b32_e64 v2, v2, 0, vcc
	v_mul_f32_e32 v92, v135, v92
	v_mul_f32_e32 v92, 0x3fb8aa3b, v92
	v_exp_f32_e32 v92, v92
	s_nop 0
	v_mul_f32_e32 v92, v92, v93
	v_cndmask_b32_e64 v106, 0, v92, s[38:39]
	v_sub_u32_e32 v92, v144, v116
	v_sub_u32_e32 v93, v144, v114
	v_cvt_f32_i32_e32 v92, v92
	v_cvt_f32_i32_e32 v93, v93
	v_cmp_ge_i32_e64 s[38:39], v144, v116
	v_mul_f32_e32 v92, v135, v92
	v_mul_f32_e32 v93, v135, v93
	v_mul_f32_e32 v92, 0x3fb8aa3b, v92
	v_mul_f32_e32 v93, 0x3fb8aa3b, v93
	v_exp_f32_e32 v92, v92
	v_exp_f32_e32 v93, v93
	s_nop 0
	v_pk_mul_f32 v[104:105], v[92:93], v[94:95]
	v_cvt_pk_bf16_f32 v92, v0, v1
	v_cvt_pk_bf16_f32 v93, v102, v103
	v_cvt_pk_bf16_f32 v94, v2, v106
	v_cvt_pk_bf16_f32 v0, v104, v105
	ds_read_b64_tr_b16 v[104:105], v126
	ds_read_b64_tr_b16 v[108:109], v126 offset:32
	ds_read_b64_tr_b16 v[102:103], v128
	ds_read_b64_tr_b16 v[106:107], v128 offset:32
	v_cndmask_b32_e64 v1, 0, v0, s[38:39]
	v_lshrrev_b32_e32 v0, 16, v0
	v_cmp_ge_i32_e64 s[38:39], v144, v114
	s_nop 1
	v_cndmask_b32_e64 v0, 0, v0, s[38:39]
	v_perm_b32 v95, v0, v1, s53
	v_add_u32_e32 v0, 17, v133
	v_cvt_f32_ubyte0_e32 v0, v0
	s_waitcnt lgkmcnt(0)
	v_mfma_f32_16x16x32_bf16 v[118:121], v[106:109], v[92:95], 0
	ds_read_b64_tr_b16 v[106:107], v128 offset:64
	ds_read_b64_tr_b16 v[108:109], v126 offset:64
	v_mul_f32_e32 v0, v135, v0
	v_mul_f32_e32 v0, 0x3fb8aa3b, v0
	s_waitcnt lgkmcnt(0)
	v_mfma_f32_16x16x32_bf16 v[146:149], v[106:109], v[92:95], 0
	ds_read_b64_tr_b16 v[106:107], v128 offset:96
	ds_read_b64_tr_b16 v[108:109], v126 offset:96
	v_exp_f32_e32 v2, v0
	v_mfma_f32_16x16x32_bf16 v[102:105], v[102:105], v[92:95], 0
	s_waitcnt lgkmcnt(0)
	v_mfma_f32_16x16x32_bf16 v[150:153], v[106:109], v[92:95], 0
	v_mfma_f32_16x16x32_bf16 v[92:95], v[20:23], v[88:91], 0
	v_mfma_f32_16x16x32_bf16 v[106:109], v[24:27], v[88:91], 0
	v_mfma_f32_16x16x32_bf16 v[88:91], v[40:43], v[88:91], 0
	v_mfma_f32_16x16x32_bf16 v[92:95], v[12:15], v[84:87], v[92:95]
	v_mfma_f32_16x16x32_bf16 v[154:157], v[16:19], v[84:87], v[106:109]
	v_mfma_f32_16x16x32_bf16 v[84:87], v[32:35], v[84:87], v[88:91]
	s_nop 5
	v_fma_f32 v108, v2, v94, v104
	v_fma_f32 v109, v2, v95, v105
	v_pk_fma_f32 v[110:111], v[2:3], v[92:93], v[102:103] op_sel_hi:[0,1,1]
	v_pk_fma_f32 v[102:103], v[2:3], v[156:157], v[120:121] op_sel_hi:[0,1,1]
	v_pk_fma_f32 v[106:107], v[2:3], v[154:155], v[118:119] op_sel_hi:[0,1,1]
	v_pk_fma_f32 v[92:93], v[2:3], v[160:161], v[148:149] op_sel_hi:[0,1,1]
	v_pk_fma_f32 v[0:1], v[2:3], v[86:87], v[152:153] op_sel_hi:[0,1,1]
	v_pk_fma_f32 v[90:91], v[2:3], v[84:85], v[150:151] op_sel_hi:[0,1,1]
	v_pk_mul_f32 v[84:85], v[108:109], v[108:109]
	v_pk_mul_f32 v[86:87], v[110:111], v[110:111]
	v_pk_fma_f32 v[94:95], v[2:3], v[158:159], v[146:147] op_sel_hi:[0,1,1]
	v_pk_mov_b32 v[88:89], v[86:87], v[84:85] op_sel:[1,0]
	v_mov_b32_e32 v87, v85
	v_pk_add_f32 v[84:85], v[88:89], v[86:87]
	v_pk_mul_f32 v[86:87], v[102:103], v[102:103]
	v_pk_mul_f32 v[88:89], v[106:107], v[106:107]
	v_mul_f32_e32 v2, v90, v90
	v_pk_mov_b32 v[104:105], v[88:89], v[86:87] op_sel:[1,0]
	v_mov_b32_e32 v89, v87
	v_pk_add_f32 v[86:87], v[104:105], v[88:89]
	v_mul_f32_e32 v88, v91, v91
	v_pk_add_f32 v[84:85], v[84:85], v[84:85] op_sel:[0,1] op_sel_hi:[1,0]
	v_pk_add_f32 v[86:87], v[86:87], v[86:87] op_sel:[0,1] op_sel_hi:[1,0]
	v_mov_b32_e32 v85, v2
	v_mov_b32_e32 v87, v88
	v_mul_f32_e32 v2, v95, v95
	v_mul_f32_e32 v89, v0, v0
	v_pk_add_f32 v[84:85], v[84:85], v[86:87]
	v_pk_fma_f32 v[86:87], v[94:95], v[94:95], v[2:3] op_sel_hi:[1,1,0]
	v_mul_f32_e32 v2, v93, v93
	v_mul_f32_e32 v104, v1, v1
	v_mov_b32_e32 v87, v89
	v_pk_fma_f32 v[88:89], v[92:93], v[92:93], v[2:3] op_sel_hi:[1,1,0]
	s_nop 0
	v_mov_b32_e32 v89, v104
	v_pk_add_f32 v[86:87], v[86:87], v[88:89]
	s_nop 0
	v_pk_add_f32 v[84:85], v[84:85], v[86:87]
	s_nop 0
	v_add_f32_e32 v2, v84, v85
	ds_bpermute_b32 v84, v138, v2
	s_waitcnt lgkmcnt(0)
	v_add_f32_e32 v2, v2, v84
	ds_bpermute_b32 v84, v137, v2
	s_waitcnt lgkmcnt(0)
	v_add_f32_e32 v2, v2, v84
	v_fmamk_f32 v2, v2, 0x3c800000, v200
	v_cmp_gt_f32_e64 s[38:39], s29, v2
	v_mul_f32_e32 v84, 0x4b800000, v2
	s_nop 0
	v_cndmask_b32_e64 v2, v2, v84, s[38:39]
	v_rsq_f32_e32 v2, v2
	s_nop 0
	v_mul_f32_e32 v84, 0x45800000, v2
	v_cndmask_b32_e64 v88, v2, v84, s[38:39]
	v_mad_u64_u32 v[84:85], s[20:21], v144, s72, v[98:99]
	v_lshl_add_u64 v[104:105], v[84:85], 0, v[96:97]
	v_mov_b64_e32 v[118:119], v[230:231]
	v_mov_b64_e32 v[84:85], v[184:185]
	v_mov_b64_e32 v[86:87], v[186:187]
	v_lshlrev_b32_e32 v2, 11, v144
	v_lshl_add_u64 v[112:113], s[40:41], 0, v[2:3]
	v_pk_mul_f32 v[110:111], v[110:111], v[88:89] op_sel_hi:[1,0]
	v_pk_mul_f32 v[108:109], v[108:109], v[88:89] op_sel_hi:[1,0]
	v_pk_mul_f32 v[106:107], v[106:107], v[88:89] op_sel_hi:[1,0]
	v_pk_mul_f32 v[102:103], v[102:103], v[88:89] op_sel_hi:[1,0]
	v_pk_mul_f32 v[94:95], v[94:95], v[88:89] op_sel_hi:[1,0]
	s_waitcnt lgkmcnt(0)
; __device__ __forceinline__ unsigned pk2(float lo, float hi) { const f32x2_t v = {lo, hi}; const bf16x2_t b = __builtin_convertvector(v, bf16x2_t); return __builtin_bit_cast(unsigned, b); }
; __device__ __forceinline__ float sigmoidf_(float x) { return __builtin_amdgcn_rcpf(1.0f + __expf(-x)); }
; template <int KIND>
; __device__ __forceinline__ void w_m3_core(const bf16x8 (&Qf)[4][2], const bf16x8 (&Kf)[4][2], const bf16x8 (&Sf)[4][2], const LAS bf16_t* vT, float lg,
;                                           const bf16_t* gsrc, const float* nw, bf16_t* ydst, int lo, int fq) {
;     ...
;         const size_t n = 16 * nb + lo;
; #pragma unroll
;         for (int eb = 0; eb < 4; ++eb) { const int e0 = 16 * eb + 4 * fq;
;             const unsigned long long gw_ = *(const unsigned long long*)(gsrc + n * NIN + e0); const f32x4 w4 = *(const f32x4*)(nw + e0);
;             const float g0 = __uint_as_float((unsigned)gw_ << 16), g1 = __uint_as_float((unsigned)gw_ & 0xffff0000u), g2 = __uint_as_float((unsigned)(gw_ >> 32) << 16), g3 = __uint_as_float((unsigned)(gw_ >> 32) & 0xffff0000u);
;             const float o0 = O[eb][0] * rs * w4[0] * (g0 * sigmoidf_(g0)), o1 = O[eb][1] * rs * w4[1] * (g1 * sigmoidf_(g1));
;             const float o2 = O[eb][2] * rs * w4[2] * (g2 * sigmoidf_(g2)), o3 = O[eb][3] * rs * w4[3] * (g3 * sigmoidf_(g3));
;             *(unsigned long long*)(ydst + n * DM + e0) = (unsigned long long)pk2(o0, o1) | ((unsigned long long)pk2(o2, o3) << 32); }
	v_lshlrev_b32_e32 v120, 16, v118
	v_mul_f32_e32 v2, 0xbfb8aa3b, v120
	v_exp_f32_e32 v2, v2
	v_and_b32_e32 v121, 0xffff0000, v118
	v_lshlrev_b32_e32 v118, 16, v119
	v_and_b32_e32 v119, 0xffff0000, v119
	v_add_f32_e32 v2, 1.0, v2
	v_rcp_f32_e32 v122, v2
	v_mul_f32_e32 v2, 0xbfb8aa3b, v121
	v_exp_f32_e32 v2, v2
	v_pk_mul_f32 v[84:85], v[84:85], v[110:111]
	v_pk_mul_f32 v[86:87], v[86:87], v[108:109]
	v_add_f32_e32 v2, 1.0, v2
	v_rcp_f32_e32 v123, v2
	v_mul_f32_e32 v2, 0xbfb8aa3b, v118
	v_exp_f32_e32 v2, v2
	v_pk_mul_f32 v[110:111], v[122:123], v[120:121]
	s_nop 0
	v_pk_mul_f32 v[84:85], v[110:111], v[84:85]
	v_add_f32_e32 v2, 1.0, v2
	v_rcp_f32_e32 v110, v2
	v_mul_f32_e32 v2, 0xbfb8aa3b, v119
	v_exp_f32_e32 v2, v2
	s_nop 0
	v_add_f32_e32 v2, 1.0, v2
	v_rcp_f32_e32 v111, v2
	s_nop 0
	v_pk_mul_f32 v[108:109], v[110:111], v[118:119]
	s_nop 0
	v_pk_mul_f32 v[86:87], v[108:109], v[86:87]
	v_cvt_pk_bf16_f32 v108, v84, v85
	v_cvt_pk_bf16_f32 v109, v86, v87
	v_lshl_add_u64 v[84:85], v[112:113], 0, v[96:97]
	global_store_dwordx2 v[84:85], v[108:109], off offset:1024
	v_mov_b64_e32 v[86:87], v[232:233]
	s_nop 0
	v_mov_b64_e32 v[108:109], v[188:189]
	v_mov_b64_e32 v[110:111], v[190:191]
	s_waitcnt lgkmcnt(0)
	v_lshlrev_b32_e32 v112, 16, v86
	v_mul_f32_e32 v2, 0xbfb8aa3b, v112
	v_exp_f32_e32 v2, v2
	v_and_b32_e32 v113, 0xffff0000, v86
	v_lshlrev_b32_e32 v86, 16, v87
	v_and_b32_e32 v87, 0xffff0000, v87
	v_add_f32_e32 v2, 1.0, v2
	v_rcp_f32_e32 v118, v2
	v_mul_f32_e32 v2, 0xbfb8aa3b, v113
	v_exp_f32_e32 v2, v2
	v_pk_mul_f32 v[106:107], v[108:109], v[106:107]
	v_pk_mul_f32 v[102:103], v[110:111], v[102:103]
	v_mul_f32_e32 v110, v92, v88
	v_add_f32_e32 v2, 1.0, v2
	v_rcp_f32_e32 v119, v2
	v_mul_f32_e32 v2, 0xbfb8aa3b, v86
	v_exp_f32_e32 v2, v2
	v_pk_mul_f32 v[108:109], v[118:119], v[112:113]
	s_nop 0
	v_pk_mul_f32 v[106:107], v[108:109], v[106:107]
	v_add_f32_e32 v2, 1.0, v2
	v_rcp_f32_e32 v108, v2
	v_mul_f32_e32 v2, 0xbfb8aa3b, v87
	v_exp_f32_e32 v2, v2
	s_nop 0
	v_add_f32_e32 v2, 1.0, v2
	v_rcp_f32_e32 v109, v2
	s_nop 0
	v_pk_mul_f32 v[86:87], v[108:109], v[86:87]
	s_nop 0
	v_pk_mul_f32 v[86:87], v[86:87], v[102:103]
	v_cvt_pk_bf16_f32 v102, v106, v107
	v_cvt_pk_bf16_f32 v103, v86, v87
	global_store_dwordx2 v[84:85], v[102:103], off offset:1056
	v_mov_b64_e32 v[86:87], v[234:235]
	v_mov_b64_e32 v[106:107], v[192:193]
	v_mov_b64_e32 v[108:109], v[194:195]
	s_waitcnt lgkmcnt(0)
	v_lshlrev_b32_e32 v102, 16, v86
	v_mul_f32_e32 v2, 0xbfb8aa3b, v102
	v_exp_f32_e32 v2, v2
	v_and_b32_e32 v103, 0xffff0000, v86
	v_lshlrev_b32_e32 v111, 16, v87
	v_and_b32_e32 v87, 0xffff0000, v87
	v_add_f32_e32 v2, 1.0, v2
	v_rcp_f32_e32 v112, v2
	v_mul_f32_e32 v2, 0xbfb8aa3b, v103
	v_exp_f32_e32 v2, v2
	v_pk_mul_f32 v[94:95], v[106:107], v[94:95]
	v_mul_f32_e32 v86, v93, v88
	v_mov_b32_e32 v92, v109
	v_add_f32_e32 v2, 1.0, v2
	v_rcp_f32_e32 v113, v2
	v_mul_f32_e32 v2, 0xbfb8aa3b, v111
	v_exp_f32_e32 v2, v2
	v_mul_f32_e32 v106, v0, v88
	v_pk_mul_f32 v[102:103], v[112:113], v[102:103]
	v_add_f32_e32 v2, 1.0, v2
	v_pk_mul_f32 v[94:95], v[102:103], v[94:95]
	v_rcp_f32_e32 v103, v2
	v_mul_f32_e32 v2, 0xbfb8aa3b, v87
	v_exp_f32_e32 v2, v2
	v_mov_b32_e32 v102, v108
	v_pk_mul_f32 v[102:103], v[102:103], v[110:111]
	v_add_f32_e32 v2, 1.0, v2
	v_rcp_f32_e32 v93, v2
	s_nop 0
	v_pk_mul_f32 v[86:87], v[92:93], v[86:87]
	v_cvt_pk_bf16_f32 v92, v94, v95
	v_mov_b32_e32 v94, v102
	v_mov_b32_e32 v95, v86
	v_mov_b32_e32 v86, v103
	v_pk_mul_f32 v[86:87], v[94:95], v[86:87]
	v_mul_f32_e32 v102, v90, v88
	v_cvt_pk_bf16_f32 v93, v86, v87
	global_store_dwordx2 v[84:85], v[92:93], off offset:1088
	v_mov_b64_e32 v[86:87], v[236:237]
	s_nop 0
	v_mov_b64_e32 v[92:93], v[196:197]
	v_mov_b64_e32 v[94:95], v[198:199]
	v_mul_f32_e32 v104, v91, v88
	s_waitcnt lgkmcnt(0)
	v_lshlrev_b32_e32 v103, 16, v86
	v_lshlrev_b32_e32 v107, 16, v87
	v_mul_f32_e32 v2, 0xbfb8aa3b, v103
	v_mul_f32_e32 v0, 0xbfb8aa3b, v107
	v_exp_f32_e32 v2, v2
	v_exp_f32_e32 v0, v0
	v_and_b32_e32 v105, 0xffff0000, v86
	v_and_b32_e32 v87, 0xffff0000, v87
	v_add_f32_e32 v2, 1.0, v2
	v_add_f32_e32 v0, 1.0, v0
	v_rcp_f32_e32 v109, v2
	v_mul_f32_e32 v2, 0xbfb8aa3b, v105
	v_mov_b32_e32 v90, v93
	v_rcp_f32_e32 v93, v0
	v_mul_f32_e32 v0, 0xbfb8aa3b, v87
	v_exp_f32_e32 v2, v2
	v_exp_f32_e32 v0, v0
	v_mul_f32_e32 v86, v1, v88
	v_mov_b32_e32 v108, v92
	v_add_f32_e32 v2, 1.0, v2
	v_add_f32_e32 v0, 1.0, v0
	v_rcp_f32_e32 v91, v2
	v_rcp_f32_e32 v1, v0
	v_mov_b32_e32 v92, v94
	v_mov_b32_e32 v0, v95
	v_pk_mul_f32 v[102:103], v[108:109], v[102:103]
	v_pk_mul_f32 v[90:91], v[90:91], v[104:105]
	v_pk_mul_f32 v[92:93], v[92:93], v[106:107]
	v_pk_mul_f32 v[0:1], v[0:1], v[86:87]
	v_mov_b32_e32 v86, v102
	v_mov_b32_e32 v87, v90
	v_mov_b32_e32 v90, v103
	v_mov_b32_e32 v88, v92
	v_mov_b32_e32 v89, v0
	v_mov_b32_e32 v0, v93
	v_pk_mul_f32 v[86:87], v[86:87], v[90:91]
	v_pk_mul_f32 v[0:1], v[88:89], v[0:1]
	v_cvt_pk_bf16_f32 v86, v86, v87
	v_cvt_pk_bf16_f32 v87, v0, v1
	global_store_dwordx2 v[84:85], v[86:87], off offset:1120
	v_sub_u32_e32 v0, v136, v124
	v_add_u32_e32 v1, v136, v143
	v_cvt_f32_i32_e32 v0, v0
	v_cvt_f32_i32_e32 v1, v1
	v_mfma_f32_16x16x32_bf16 v[84:87], v[64:67], v[80:83], 0
	v_sub_u32_e32 v2, v136, v142
	v_mul_f32_e32 v0, v135, v0
	v_mul_f32_e32 v1, v135, v1
	v_cvt_f32_i32_e32 v2, v2
	v_mul_f32_e32 v0, 0x3fb8aa3b, v0
	v_mul_f32_e32 v1, 0x3fb8aa3b, v1
	v_mfma_f32_16x16x32_bf16 v[84:87], v[72:75], v[76:79], v[84:87]
	v_exp_f32_e32 v0, v0
	v_exp_f32_e32 v1, v1
	v_mul_f32_e32 v2, v135, v2
	v_mul_f32_e32 v2, 0x3fb8aa3b, v2
	s_nop 3
	v_pk_mul_f32 v[0:1], v[0:1], v[84:85]
	v_exp_f32_e32 v84, v2
	v_sub_u32_e32 v2, v136, v141
	v_cvt_f32_i32_e32 v2, v2
	v_mul_f32_e32 v2, v135, v2
	v_mul_f32_e32 v2, 0x3fb8aa3b, v2
	v_exp_f32_e32 v85, v2
	v_sub_u32_e32 v2, v136, v114
	v_cvt_f32_i32_e32 v2, v2
	v_pk_mul_f32 v[88:89], v[84:85], v[86:87]
	v_mfma_f32_16x16x32_bf16 v[84:87], v[60:63], v[80:83], 0
	v_mul_f32_e32 v2, v135, v2
	v_mul_f32_e32 v2, 0x3fb8aa3b, v2
	v_exp_f32_e32 v91, v2
	v_sub_u32_e32 v2, v136, v140
	v_cvt_f32_i32_e32 v2, v2
	v_mfma_f32_16x16x32_bf16 v[84:87], v[68:71], v[76:79], v[84:87]
	v_mul_f32_e32 v2, v135, v2
	v_mul_f32_e32 v2, 0x3fb8aa3b, v2
	v_exp_f32_e32 v92, v2
	v_sub_u32_e32 v2, v136, v115
	v_cvt_f32_i32_e32 v2, v2
	v_mul_f32_e32 v2, v135, v2
	v_mul_f32_e32 v2, 0x3fb8aa3b, v2
	v_exp_f32_e32 v93, v2
	v_sub_u32_e32 v2, v136, v116
	v_cvt_f32_i32_e32 v2, v2
	v_pk_mul_f32 v[92:93], v[92:93], v[84:85]
	v_cvt_pk_bf16_f32 v85, v88, v89
	v_mul_f32_e32 v2, v135, v2
	v_mul_f32_e32 v2, 0x3fb8aa3b, v2
	v_exp_f32_e32 v90, v2
	v_cvt_pk_bf16_f32 v84, v0, v1
	v_pk_mul_f32 v[90:91], v[90:91], v[86:87]
	v_cvt_pk_bf16_f32 v86, v92, v93
	v_cvt_pk_bf16_f32 v87, v90, v91
	ds_read_b64_tr_b16 v[90:91], v126
	ds_read_b64_tr_b16 v[94:95], v126 offset:32
	ds_read_b64_tr_b16 v[88:89], v128
	ds_read_b64_tr_b16 v[92:93], v128 offset:32
	ds_read_b64_tr_b16 v[102:103], v128 offset:64
	ds_read_b64_tr_b16 v[104:105], v126 offset:64
	ds_read_b64_tr_b16 v[106:107], v128 offset:96
	ds_read_b64_tr_b16 v[108:109], v126 offset:96
	s_waitcnt lgkmcnt(0)
; template <int KIND>
; __device__ __forceinline__ void w_m3_core(const bf16x8 (&Qf)[4][2], const bf16x8 (&Kf)[4][2], const bf16x8 (&Sf)[4][2], const LAS bf16_t* vT, float lg,
;                                           const bf16_t* gsrc, const float* nw, bf16_t* ydst, int lo, int fq) {
;     ...
;             float pv[8];
; #pragma unroll
;             for (int hh = 0; hh < 2; ++hh) { const int mb = 2 * kk2 + hh;
;                 if (mb <= nb) { f32x4 s = {0.f, 0.f, 0.f, 0.f};
;                     s = __builtin_amdgcn_mfma_f32_16x16x32_bf16(Kf[mb][0], Qf[nb][0], s, 0, 0, 0); s = __builtin_amdgcn_mfma_f32_16x16x32_bf16(Kf[mb][1], Qf[nb][1], s, 0, 0, 0);
; #pragma unroll
;                     for (int r = 0; r < 4; ++r) { const int m = 16 * mb + 4 * fq + r, n = 16 * nb + lo; float v = s[r];
;                         if (KIND == 0) v *= __expf((float)(n - m) * lg);
;                         if (mb == nb) v = (m <= n) ? v : 0.f;
;                         pv[4 * hh + r] = v; }
;                 } else {
; #pragma unroll
;                     for (int r = 0; r < 4; ++r) pv[4 * hh + r] = 0.f; }
;             }
;             const bf16x8 Pf = pack_frag(pv);
; #pragma unroll
;             for (int eb = 0; eb < 4; ++eb)
;                 O[eb] = __builtin_amdgcn_mfma_f32_16x16x32_bf16(tr_frag(vT, 32 * kk2 + 4 * fq, 32 * kk2 + 16 + 4 * fq, 16 * eb, lo), Pf, O[eb], 0, 0, 0);
;         }
; #pragma unroll
;         for (int kk = 0; kk < 2; ++kk)
; #pragma unroll
;             for (int eb = 0; eb < 4; ++eb) O2[eb] = __builtin_amdgcn_mfma_f32_16x16x32_bf16(Sf[eb][kk], Qf[nb][kk], O2[eb], 0, 0, 0);
;         const float osc = KIND == 0 ? __expf((float)(16 * nb + lo + 1) * lg) : 1.0f;
; #pragma unroll
;         for (int eb = 0; eb < 4; ++eb) O[eb] = O[eb] + O2[eb] * osc;
;         float ss = 0.f;
; #pragma unroll
;         for (int eb = 0; eb < 4; ++eb) ss += (O[eb][0] * O[eb][0] + O[eb][1] * O[eb][1]) + (O[eb][2] * O[eb][2] + O[eb][3] * O[eb][3]);
;         { const int ln = (fq << 4) | lo; ss += bperm_f(ln ^ 16, ss); ss += bperm_f(ln ^ 32, ss); }
;         const float rs = rsqrtf(ss * (1.0f / 64.0f) + EPS);
;         const size_t n = 16 * nb + lo;
; #pragma unroll
;         for (int eb = 0; eb < 4; ++eb) { const int e0 = 16 * eb + 4 * fq;
;             const unsigned long long gw_ = *(const unsigned long long*)(gsrc + n * NIN + e0); const f32x4 w4 = *(const f32x4*)(nw + e0);
	v_mfma_f32_16x16x32_bf16 v[88:91], v[88:91], v[84:87], 0
	v_mfma_f32_16x16x32_bf16 v[92:95], v[92:95], v[84:87], 0
	v_mfma_f32_16x16x32_bf16 v[102:105], v[102:105], v[84:87], 0
	v_mfma_f32_16x16x32_bf16 v[84:87], v[106:109], v[84:87], 0
	v_mfma_f32_16x16x32_bf16 v[106:109], v[44:47], v[80:83], 0
	v_mfma_f32_16x16x32_bf16 v[108:111], v[48:51], v[76:79], v[106:109]
	s_nop 6
	v_add_u32_e32 v107, 33, v124
	v_mul_f32_e32 v0, v139, v108
	v_cndmask_b32_e64 v2, v0, 0, vcc
	v_sub_u32_e32 v0, v136, v107
	v_cvt_f32_i32_e32 v0, v0
	v_cmp_ge_i32_e64 s[38:39], v136, v107
	v_add_u32_e32 v106, 35, v124
	v_add_u32_e32 v108, 34, v124
	v_mul_f32_e32 v0, v135, v0
	v_mul_f32_e32 v0, 0x3fb8aa3b, v0
	v_exp_f32_e32 v0, v0
	v_sub_u32_e32 v1, v136, v106
	v_cvt_f32_i32_e32 v1, v1
	v_mul_f32_e32 v0, v0, v109
	v_cndmask_b32_e64 v109, 0, v0, s[38:39]
	v_sub_u32_e32 v0, v136, v108
	v_cvt_f32_i32_e32 v0, v0
	v_mul_f32_e32 v1, v135, v1
	v_mul_f32_e32 v1, 0x3fb8aa3b, v1
	v_exp_f32_e32 v1, v1
	v_mul_f32_e32 v0, v135, v0
	v_mul_f32_e32 v0, 0x3fb8aa3b, v0
	v_exp_f32_e32 v0, v0
	v_cmp_ge_i32_e64 s[38:39], v136, v108
	v_pk_mul_f32 v[110:111], v[0:1], v[110:111]
	s_nop 0
	v_cvt_pk_bf16_f32 v1, v110, v111
	ds_read_b64_tr_b16 v[110:111], v128 offset:4608
	ds_read_b64_tr_b16 v[112:113], v126 offset:4608
	v_cvt_pk_bf16_f32 v0, v2, v109
	v_cndmask_b32_e64 v2, 0, v1, s[38:39]
	v_lshrrev_b32_e32 v1, 16, v1
	v_cmp_ge_i32_e64 s[38:39], v136, v106
	s_nop 1
	v_cndmask_b32_e64 v1, 0, v1, s[38:39]
	v_perm_b32 v1, v1, v2, s53
	v_mov_b32_e32 v2, v3
	s_waitcnt lgkmcnt(0)
	s_nop 0
	v_mfma_f32_16x16x32_bf16 v[88:91], v[110:113], v[0:3], v[88:91]
	ds_read_b64_tr_b16 v[110:111], v128 offset:4640
	ds_read_b64_tr_b16 v[112:113], v126 offset:4640
	s_waitcnt lgkmcnt(0)
	v_mfma_f32_16x16x32_bf16 v[110:113], v[110:113], v[0:3], v[92:95]
	s_nop 2
	ds_read_b64_tr_b16 v[92:93], v128 offset:4672
	ds_read_b64_tr_b16 v[94:95], v126 offset:4672
	s_waitcnt lgkmcnt(0)
	v_mfma_f32_16x16x32_bf16 v[118:121], v[92:95], v[0:3], v[102:105]
	ds_read_b64_tr_b16 v[92:93], v128 offset:4704
	ds_read_b64_tr_b16 v[94:95], v126 offset:4704
	s_waitcnt lgkmcnt(0)
	v_mfma_f32_16x16x32_bf16 v[144:147], v[92:95], v[0:3], v[84:87]
	v_add_u32_e32 v0, 33, v133
	v_cvt_f32_ubyte0_e32 v0, v0
	v_mul_f32_e32 v0, v135, v0
	v_mfma_f32_16x16x32_bf16 v[84:87], v[20:23], v[80:83], 0
	v_mul_f32_e32 v0, 0x3fb8aa3b, v0
	v_exp_f32_e32 v2, v0
	v_mfma_f32_16x16x32_bf16 v[92:95], v[24:27], v[80:83], 0
	v_mfma_f32_16x16x32_bf16 v[102:105], v[36:39], v[80:83], 0
	v_mfma_f32_16x16x32_bf16 v[80:83], v[40:43], v[80:83], 0
	v_mfma_f32_16x16x32_bf16 v[84:87], v[12:15], v[76:79], v[84:87]
	v_mfma_f32_16x16x32_bf16 v[148:151], v[16:19], v[76:79], v[92:95]
	v_mfma_f32_16x16x32_bf16 v[152:155], v[28:31], v[76:79], v[102:105]
	s_nop 5
	v_fma_f32 v94, v2, v86, v90
	v_fma_f32 v95, v2, v87, v91
	v_pk_fma_f32 v[92:93], v[2:3], v[148:149], v[110:111] op_sel_hi:[0,1,1]
	v_mfma_f32_16x16x32_bf16 v[76:79], v[32:35], v[76:79], v[80:83]
	v_fma_f32 v102, v2, v84, v88
	v_fma_f32 v103, v2, v85, v89
	v_pk_fma_f32 v[88:89], v[2:3], v[150:151], v[112:113] op_sel_hi:[0,1,1]
	v_pk_fma_f32 v[84:85], v[2:3], v[154:155], v[120:121] op_sel_hi:[0,1,1]
	v_pk_fma_f32 v[86:87], v[2:3], v[152:153], v[118:119] op_sel_hi:[0,1,1]
	s_nop 2
	v_pk_fma_f32 v[0:1], v[2:3], v[78:79], v[146:147] op_sel_hi:[0,1,1]
	v_pk_fma_f32 v[82:83], v[2:3], v[76:77], v[144:145] op_sel_hi:[0,1,1]
	v_pk_mul_f32 v[76:77], v[94:95], v[94:95]
	v_pk_mul_f32 v[78:79], v[102:103], v[102:103]
	v_mul_f32_e32 v2, v82, v82
	v_pk_mov_b32 v[80:81], v[78:79], v[76:77] op_sel:[1,0]
	v_mov_b32_e32 v79, v77
	v_pk_add_f32 v[76:77], v[80:81], v[78:79]
	v_pk_mul_f32 v[78:79], v[88:89], v[88:89]
	v_pk_mul_f32 v[80:81], v[92:93], v[92:93]
	v_pk_add_f32 v[76:77], v[76:77], v[76:77] op_sel:[0,1] op_sel_hi:[1,0]
	v_pk_mov_b32 v[90:91], v[80:81], v[78:79] op_sel:[1,0]
	v_mov_b32_e32 v81, v79
	v_pk_add_f32 v[78:79], v[90:91], v[80:81]
	v_mul_f32_e32 v80, v83, v83
	v_pk_add_f32 v[78:79], v[78:79], v[78:79] op_sel:[0,1] op_sel_hi:[1,0]
	v_mov_b32_e32 v77, v2
	v_mov_b32_e32 v79, v80
	v_mul_f32_e32 v2, v87, v87
	v_mul_f32_e32 v81, v0, v0
	v_pk_add_f32 v[76:77], v[76:77], v[78:79]
	v_pk_fma_f32 v[78:79], v[86:87], v[86:87], v[2:3] op_sel_hi:[1,1,0]
	v_mul_f32_e32 v2, v85, v85
	v_mul_f32_e32 v90, v1, v1
	v_mov_b32_e32 v79, v81
	v_pk_fma_f32 v[80:81], v[84:85], v[84:85], v[2:3] op_sel_hi:[1,1,0]
	s_nop 0
	v_mov_b32_e32 v81, v90
	v_pk_add_f32 v[78:79], v[78:79], v[80:81]
	s_nop 0
	v_pk_add_f32 v[76:77], v[76:77], v[78:79]
	s_nop 0
	v_add_f32_e32 v2, v76, v77
	ds_bpermute_b32 v76, v138, v2
	s_waitcnt lgkmcnt(0)
	v_add_f32_e32 v2, v2, v76
	ds_bpermute_b32 v76, v137, v2
	s_waitcnt lgkmcnt(0)
	v_add_f32_e32 v2, v2, v76
	v_fmamk_f32 v2, v2, 0x3c800000, v200
	v_cmp_gt_f32_e64 s[38:39], s29, v2
	v_mul_f32_e32 v76, 0x4b800000, v2
	s_nop 0
	v_cndmask_b32_e64 v2, v2, v76, s[38:39]
	v_rsq_f32_e32 v2, v2
	s_nop 0
	v_mul_f32_e32 v76, 0x45800000, v2
	v_cndmask_b32_e64 v80, v2, v76, s[38:39]
	v_mad_u64_u32 v[76:77], s[20:21], v136, s72, v[98:99]
	v_lshl_add_u64 v[90:91], v[76:77], 0, v[96:97]
	v_mov_b64_e32 v[110:111], v[238:239]
	v_mov_b64_e32 v[76:77], v[184:185]
	v_mov_b64_e32 v[78:79], v[186:187]
	v_lshlrev_b32_e32 v2, 11, v136
	v_lshl_add_u64 v[104:105], s[40:41], 0, v[2:3]
	v_pk_mul_f32 v[102:103], v[102:103], v[80:81] op_sel_hi:[1,0]
	v_pk_mul_f32 v[94:95], v[94:95], v[80:81] op_sel_hi:[1,0]
	v_pk_mul_f32 v[92:93], v[92:93], v[80:81] op_sel_hi:[1,0]
	v_pk_mul_f32 v[88:89], v[88:89], v[80:81] op_sel_hi:[1,0]
	v_pk_mul_f32 v[86:87], v[86:87], v[80:81] op_sel_hi:[1,0]
	s_waitcnt lgkmcnt(0)
; __device__ __forceinline__ unsigned pk2(float lo, float hi) { const f32x2_t v = {lo, hi}; const bf16x2_t b = __builtin_convertvector(v, bf16x2_t); return __builtin_bit_cast(unsigned, b); }
; __device__ __forceinline__ float sigmoidf_(float x) { return __builtin_amdgcn_rcpf(1.0f + __expf(-x)); }
; template <int KIND>
; __device__ __forceinline__ void w_m3_core(const bf16x8 (&Qf)[4][2], const bf16x8 (&Kf)[4][2], const bf16x8 (&Sf)[4][2], const LAS bf16_t* vT, float lg,
;                                           const bf16_t* gsrc, const float* nw, bf16_t* ydst, int lo, int fq) {
;     ...
;         const size_t n = 16 * nb + lo;
; #pragma unroll
;         for (int eb = 0; eb < 4; ++eb) { const int e0 = 16 * eb + 4 * fq;
;             const unsigned long long gw_ = *(const unsigned long long*)(gsrc + n * NIN + e0); const f32x4 w4 = *(const f32x4*)(nw + e0);
;             const float g0 = __uint_as_float((unsigned)gw_ << 16), g1 = __uint_as_float((unsigned)gw_ & 0xffff0000u), g2 = __uint_as_float((unsigned)(gw_ >> 32) << 16), g3 = __uint_as_float((unsigned)(gw_ >> 32) & 0xffff0000u);
;             const float o0 = O[eb][0] * rs * w4[0] * (g0 * sigmoidf_(g0)), o1 = O[eb][1] * rs * w4[1] * (g1 * sigmoidf_(g1));
;             const float o2 = O[eb][2] * rs * w4[2] * (g2 * sigmoidf_(g2)), o3 = O[eb][3] * rs * w4[3] * (g3 * sigmoidf_(g3));
;             *(unsigned long long*)(ydst + n * DM + e0) = (unsigned long long)pk2(o0, o1) | ((unsigned long long)pk2(o2, o3) << 32); }
	v_lshlrev_b32_e32 v112, 16, v110
	v_mul_f32_e32 v2, 0xbfb8aa3b, v112
	v_exp_f32_e32 v2, v2
	v_and_b32_e32 v113, 0xffff0000, v110
	v_lshlrev_b32_e32 v110, 16, v111
	v_and_b32_e32 v111, 0xffff0000, v111
	v_add_f32_e32 v2, 1.0, v2
	v_rcp_f32_e32 v118, v2
	v_mul_f32_e32 v2, 0xbfb8aa3b, v113
	v_exp_f32_e32 v2, v2
	v_pk_mul_f32 v[76:77], v[76:77], v[102:103]
	v_pk_mul_f32 v[78:79], v[78:79], v[94:95]
	v_add_f32_e32 v2, 1.0, v2
	v_rcp_f32_e32 v119, v2
	v_mul_f32_e32 v2, 0xbfb8aa3b, v110
	v_exp_f32_e32 v2, v2
	v_pk_mul_f32 v[102:103], v[118:119], v[112:113]
	s_nop 0
	v_pk_mul_f32 v[76:77], v[102:103], v[76:77]
	v_add_f32_e32 v2, 1.0, v2
	v_rcp_f32_e32 v102, v2
	v_mul_f32_e32 v2, 0xbfb8aa3b, v111
	v_exp_f32_e32 v2, v2
	s_nop 0
	v_add_f32_e32 v2, 1.0, v2
	v_rcp_f32_e32 v103, v2
	s_nop 0
	v_pk_mul_f32 v[94:95], v[102:103], v[110:111]
	s_nop 0
	v_pk_mul_f32 v[78:79], v[94:95], v[78:79]
	v_cvt_pk_bf16_f32 v94, v76, v77
	v_cvt_pk_bf16_f32 v95, v78, v79
	v_lshl_add_u64 v[76:77], v[104:105], 0, v[96:97]
	global_store_dwordx2 v[76:77], v[94:95], off offset:1024
	v_mov_b64_e32 v[78:79], v[240:241]
	v_mov_b64_e32 v[102:103], v[188:189]
	v_mov_b64_e32 v[104:105], v[190:191]
	s_waitcnt lgkmcnt(0)
	v_lshlrev_b32_e32 v94, 16, v78
	v_mul_f32_e32 v2, 0xbfb8aa3b, v94
	v_exp_f32_e32 v2, v2
	v_and_b32_e32 v95, 0xffff0000, v78
	v_lshlrev_b32_e32 v78, 16, v79
	v_and_b32_e32 v79, 0xffff0000, v79
	v_add_f32_e32 v2, 1.0, v2
	v_rcp_f32_e32 v110, v2
	v_mul_f32_e32 v2, 0xbfb8aa3b, v95
	v_exp_f32_e32 v2, v2
	v_pk_mul_f32 v[92:93], v[102:103], v[92:93]
	v_pk_mul_f32 v[88:89], v[104:105], v[88:89]
	v_mul_f32_e32 v102, v84, v80
	v_add_f32_e32 v2, 1.0, v2
	v_rcp_f32_e32 v111, v2
	v_mul_f32_e32 v2, 0xbfb8aa3b, v78
	v_exp_f32_e32 v2, v2
	v_pk_mul_f32 v[94:95], v[110:111], v[94:95]
	s_nop 0
	v_pk_mul_f32 v[92:93], v[94:95], v[92:93]
	v_add_f32_e32 v2, 1.0, v2
	v_rcp_f32_e32 v94, v2
	v_mul_f32_e32 v2, 0xbfb8aa3b, v79
	v_exp_f32_e32 v2, v2
	s_nop 0
	v_add_f32_e32 v2, 1.0, v2
	v_rcp_f32_e32 v95, v2
	s_nop 0
	v_pk_mul_f32 v[78:79], v[94:95], v[78:79]
	s_nop 0
	v_pk_mul_f32 v[78:79], v[78:79], v[88:89]
	v_cvt_pk_bf16_f32 v88, v92, v93
	v_cvt_pk_bf16_f32 v89, v78, v79
	global_store_dwordx2 v[76:77], v[88:89], off offset:1056
	v_mov_b64_e32 v[78:79], v[242:243]
	v_mov_b64_e32 v[92:93], v[192:193]
	v_mov_b64_e32 v[94:95], v[194:195]
	s_waitcnt lgkmcnt(0)
	v_lshlrev_b32_e32 v88, 16, v78
	v_mul_f32_e32 v2, 0xbfb8aa3b, v88
	v_exp_f32_e32 v2, v2
	v_and_b32_e32 v89, 0xffff0000, v78
	v_lshlrev_b32_e32 v103, 16, v79
	v_and_b32_e32 v79, 0xffff0000, v79
	v_add_f32_e32 v2, 1.0, v2
	v_rcp_f32_e32 v104, v2
	v_mul_f32_e32 v2, 0xbfb8aa3b, v89
	v_exp_f32_e32 v2, v2
	v_pk_mul_f32 v[86:87], v[92:93], v[86:87]
	v_mul_f32_e32 v78, v85, v80
	v_mov_b32_e32 v84, v95
	v_add_f32_e32 v2, 1.0, v2
	v_rcp_f32_e32 v105, v2
	v_mul_f32_e32 v2, 0xbfb8aa3b, v103
	v_exp_f32_e32 v2, v2
	v_mul_f32_e32 v92, v0, v80
	v_pk_mul_f32 v[88:89], v[104:105], v[88:89]
	v_add_f32_e32 v2, 1.0, v2
	v_pk_mul_f32 v[86:87], v[88:89], v[86:87]
	v_rcp_f32_e32 v89, v2
	v_mul_f32_e32 v2, 0xbfb8aa3b, v79
	v_exp_f32_e32 v2, v2
	v_mov_b32_e32 v88, v94
	v_pk_mul_f32 v[88:89], v[88:89], v[102:103]
	v_add_f32_e32 v2, 1.0, v2
	v_rcp_f32_e32 v85, v2
	s_nop 0
	v_pk_mul_f32 v[78:79], v[84:85], v[78:79]
	v_cvt_pk_bf16_f32 v84, v86, v87
	v_mov_b32_e32 v86, v88
	v_mov_b32_e32 v87, v78
	v_mov_b32_e32 v78, v89
	v_pk_mul_f32 v[78:79], v[86:87], v[78:79]
	v_mul_f32_e32 v88, v82, v80
	v_cvt_pk_bf16_f32 v85, v78, v79
	global_store_dwordx2 v[76:77], v[84:85], off offset:1088
	v_mov_b64_e32 v[78:79], v[244:245]
	s_nop 0
	v_mov_b64_e32 v[84:85], v[196:197]
	v_mov_b64_e32 v[86:87], v[198:199]
	v_mul_f32_e32 v90, v83, v80
	s_waitcnt lgkmcnt(0)
	v_lshlrev_b32_e32 v89, 16, v78
	v_lshlrev_b32_e32 v93, 16, v79
	v_mul_f32_e32 v2, 0xbfb8aa3b, v89
	v_mul_f32_e32 v0, 0xbfb8aa3b, v93
	v_exp_f32_e32 v2, v2
	v_exp_f32_e32 v0, v0
	v_and_b32_e32 v91, 0xffff0000, v78
	v_and_b32_e32 v79, 0xffff0000, v79
	v_add_f32_e32 v2, 1.0, v2
	v_add_f32_e32 v0, 1.0, v0
	v_rcp_f32_e32 v95, v2
	v_mul_f32_e32 v2, 0xbfb8aa3b, v91
	v_mov_b32_e32 v82, v85
	v_rcp_f32_e32 v85, v0
	v_mul_f32_e32 v0, 0xbfb8aa3b, v79
	v_exp_f32_e32 v2, v2
	v_exp_f32_e32 v0, v0
	v_mul_f32_e32 v78, v1, v80
	v_mov_b32_e32 v94, v84
	v_add_f32_e32 v2, 1.0, v2
	v_add_f32_e32 v0, 1.0, v0
	v_rcp_f32_e32 v83, v2
	v_rcp_f32_e32 v1, v0
	v_mov_b32_e32 v84, v86
	v_mov_b32_e32 v0, v87
	v_pk_mul_f32 v[88:89], v[94:95], v[88:89]
	v_pk_mul_f32 v[82:83], v[82:83], v[90:91]
	v_pk_mul_f32 v[84:85], v[84:85], v[92:93]
	v_pk_mul_f32 v[0:1], v[0:1], v[78:79]
	v_mov_b32_e32 v78, v88
	v_mov_b32_e32 v79, v82
	v_mov_b32_e32 v82, v89
	v_mov_b32_e32 v80, v84
	v_mov_b32_e32 v81, v0
	v_mov_b32_e32 v0, v85
	v_pk_mul_f32 v[78:79], v[78:79], v[82:83]
	v_pk_mul_f32 v[0:1], v[80:81], v[0:1]
	v_cvt_pk_bf16_f32 v78, v78, v79
	v_cvt_pk_bf16_f32 v79, v0, v1
	global_store_dwordx2 v[76:77], v[78:79], off offset:1120
	v_sub_u32_e32 v2, v134, v124
	v_add_u32_e32 v1, v134, v143
	v_cvt_f32_i32_e32 v0, v2
	v_cvt_f32_i32_e32 v1, v1
	v_mfma_f32_16x16x32_bf16 v[64:67], v[64:67], v[8:11], 0
	v_mul_f32_e32 v0, v135, v0
	v_mul_f32_e32 v1, v135, v1
	v_mul_f32_e32 v0, 0x3fb8aa3b, v0
	v_mul_f32_e32 v1, 0x3fb8aa3b, v1
	v_mfma_f32_16x16x32_bf16 v[64:67], v[72:75], v[4:7], v[64:67]
	v_exp_f32_e32 v0, v0
	v_exp_f32_e32 v1, v1
	v_mfma_f32_16x16x32_bf16 v[60:63], v[60:63], v[8:11], 0
	v_mfma_f32_16x16x32_bf16 v[60:63], v[68:71], v[4:7], v[60:63]
	s_nop 3
	v_mul_f32_e64 v0, v0, v64
	v_mul_f32_e64 v1, v1, v65
	v_sub_u32_e32 v64, v134, v142
	v_cvt_pk_bf16_f32 v68, v0, v1
	v_subrev_u32_e32 v0, 32, v2
	v_sub_u32_e32 v1, v134, v107
	v_cvt_f32_i32_e32 v0, v0
	v_cvt_f32_i32_e32 v1, v1
; __device__ __forceinline__ float bperm_f(int src_lane, float v) { return __builtin_bit_cast(float, __builtin_amdgcn_ds_bpermute(src_lane << 2, __builtin_bit_cast(int, v))); }
; template <int KIND>
; __device__ __forceinline__ void w_m3_core(const bf16x8 (&Qf)[4][2], const bf16x8 (&Kf)[4][2], const bf16x8 (&Sf)[4][2], const LAS bf16_t* vT, float lg,
;                                           const bf16_t* gsrc, const float* nw, bf16_t* ydst, int lo, int fq) {
;     ...
;             float pv[8];
; #pragma unroll
;             for (int hh = 0; hh < 2; ++hh) { const int mb = 2 * kk2 + hh;
;                 if (mb <= nb) { f32x4 s = {0.f, 0.f, 0.f, 0.f};
;                     s = __builtin_amdgcn_mfma_f32_16x16x32_bf16(Kf[mb][0], Qf[nb][0], s, 0, 0, 0); s = __builtin_amdgcn_mfma_f32_16x16x32_bf16(Kf[mb][1], Qf[nb][1], s, 0, 0, 0);
; #pragma unroll
;                     for (int r = 0; r < 4; ++r) { const int m = 16 * mb + 4 * fq + r, n = 16 * nb + lo; float v = s[r];
;                         if (KIND == 0) v *= __expf((float)(n - m) * lg);
;                         if (mb == nb) v = (m <= n) ? v : 0.f;
;                         pv[4 * hh + r] = v; }
;                 } else {
; #pragma unroll
;                     for (int r = 0; r < 4; ++r) pv[4 * hh + r] = 0.f; }
;             }
;             const bf16x8 Pf = pack_frag(pv);
; #pragma unroll
;             for (int eb = 0; eb < 4; ++eb)
;                 O[eb] = __builtin_amdgcn_mfma_f32_16x16x32_bf16(tr_frag(vT, 32 * kk2 + 4 * fq, 32 * kk2 + 16 + 4 * fq, 16 * eb, lo), Pf, O[eb], 0, 0, 0);
;         }
; #pragma unroll
;         for (int kk = 0; kk < 2; ++kk)
; #pragma unroll
;             for (int eb = 0; eb < 4; ++eb) O2[eb] = __builtin_amdgcn_mfma_f32_16x16x32_bf16(Sf[eb][kk], Qf[nb][kk], O2[eb], 0, 0, 0);
;         const float osc = KIND == 0 ? __expf((float)(16 * nb + lo + 1) * lg) : 1.0f;
; #pragma unroll
;         for (int eb = 0; eb < 4; ++eb) O[eb] = O[eb] + O2[eb] * osc;
;         float ss = 0.f;
; #pragma unroll
;         for (int eb = 0; eb < 4; ++eb) ss += (O[eb][0] * O[eb][0] + O[eb][1] * O[eb][1]) + (O[eb][2] * O[eb][2] + O[eb][3] * O[eb][3]);
;         { const int ln = (fq << 4) | lo; ss += bperm_f(ln ^ 16, ss); ss += bperm_f(ln ^ 32, ss); }
;         const float rs = rsqrtf(ss * (1.0f / 64.0f) + EPS);
	v_mfma_f32_16x16x32_bf16 v[44:47], v[44:47], v[8:11], 0
	v_sub_u32_e32 v2, v134, v108
	v_mul_f32_e32 v0, v135, v0
	v_mul_f32_e32 v1, v135, v1
	v_cvt_f32_i32_e32 v2, v2
	v_mul_f32_e32 v0, 0x3fb8aa3b, v0
	v_mul_f32_e32 v1, 0x3fb8aa3b, v1
	v_mfma_f32_16x16x32_bf16 v[44:47], v[48:51], v[4:7], v[44:47]
	v_exp_f32_e32 v0, v0
	v_exp_f32_e32 v1, v1
	v_mul_f32_e32 v2, v135, v2
	v_mul_f32_e32 v2, 0x3fb8aa3b, v2
	v_sub_u32_e32 v65, v134, v141
	s_nop 2
	v_pk_mul_f32 v[0:1], v[0:1], v[44:45]
	v_exp_f32_e32 v44, v2
	v_sub_u32_e32 v2, v134, v106
	v_cvt_f32_i32_e32 v2, v2
	v_cvt_f32_i32_e32 v64, v64
	v_cvt_f32_i32_e32 v65, v65
	v_mfma_f32_16x16x32_bf16 v[20:23], v[20:23], v[8:11], 0
	v_mul_f32_e32 v2, v135, v2
	v_mul_f32_e32 v2, 0x3fb8aa3b, v2
	v_exp_f32_e32 v45, v2
	v_mul_f32_e32 v64, v135, v64
	v_mul_f32_e32 v65, v135, v65
	v_mul_f32_e32 v64, 0x3fb8aa3b, v64
	v_pk_mul_f32 v[48:49], v[44:45], v[46:47]
	v_mfma_f32_16x16x32_bf16 v[44:47], v[52:55], v[8:11], 0
	v_mul_f32_e32 v65, 0x3fb8aa3b, v65
	v_exp_f32_e32 v64, v64
	v_exp_f32_e32 v65, v65
	v_mfma_f32_16x16x32_bf16 v[44:47], v[56:59], v[4:7], v[44:47]
	v_mul_f32_e64 v64, v64, v66
	v_mul_f32_e64 v65, v65, v67
	v_sub_u32_e32 v66, v134, v140
	v_sub_u32_e32 v67, v134, v115
	s_nop 3
	v_mul_f32_e32 v2, v139, v44
	v_add_u32_e32 v44, 49, v124
	v_sub_u32_e32 v50, v134, v44
	v_cvt_f32_i32_e32 v50, v50
	v_cvt_f32_i32_e32 v66, v66
	v_cvt_f32_i32_e32 v67, v67
	v_cndmask_b32_e64 v2, v2, 0, vcc
	v_mul_f32_e32 v50, v135, v50
	v_mul_f32_e32 v50, 0x3fb8aa3b, v50
	v_exp_f32_e32 v50, v50
	v_cmp_ge_i32_e32 vcc, v134, v44
	v_add_u32_e32 v44, 50, v124
	v_mul_f32_e32 v66, v135, v66
	v_mul_f32_e32 v45, v50, v45
	v_cndmask_b32_e32 v50, 0, v45, vcc
	v_sub_u32_e32 v45, v134, v44
	v_cvt_f32_i32_e32 v45, v45
	v_mul_f32_e32 v67, v135, v67
	v_mul_f32_e32 v66, 0x3fb8aa3b, v66
	v_mul_f32_e32 v67, 0x3fb8aa3b, v67
	v_exp_f32_e32 v66, v66
	v_exp_f32_e32 v67, v67
	v_mul_f32_e32 v45, v135, v45
	v_mul_f32_e32 v45, 0x3fb8aa3b, v45
	v_exp_f32_e32 v45, v45
	v_pk_mul_f32 v[60:61], v[66:67], v[60:61]
	v_sub_u32_e32 v66, v134, v116
	v_sub_u32_e32 v67, v134, v114
	v_cvt_f32_i32_e32 v66, v66
	v_cvt_f32_i32_e32 v67, v67
	v_mul_f32_e32 v45, v45, v46
	v_cmp_ge_i32_e32 vcc, v134, v44
	v_add_u32_e32 v44, 51, v124
	v_mul_f32_e32 v66, v135, v66
	v_cndmask_b32_e32 v51, 0, v45, vcc
	v_sub_u32_e32 v45, v134, v44
	v_mul_f32_e32 v67, v135, v67
	v_cvt_f32_i32_e32 v45, v45
	v_mul_f32_e32 v66, 0x3fb8aa3b, v66
	v_mul_f32_e32 v67, 0x3fb8aa3b, v67
	v_exp_f32_e32 v66, v66
	v_exp_f32_e32 v67, v67
	v_mul_f32_e32 v45, v135, v45
	v_mul_f32_e32 v45, 0x3fb8aa3b, v45
	v_exp_f32_e32 v45, v45
	v_pk_mul_f32 v[62:63], v[66:67], v[62:63]
	v_cvt_pk_bf16_f32 v69, v64, v65
	v_cvt_pk_bf16_f32 v70, v60, v61
	v_cvt_pk_bf16_f32 v71, v62, v63
	ds_read_b64_tr_b16 v[62:63], v126
	ds_read_b64_tr_b16 v[66:67], v126 offset:32
	ds_read_b64_tr_b16 v[60:61], v128
	ds_read_b64_tr_b16 v[64:65], v128 offset:32
	v_mul_f32_e32 v45, v45, v47
	v_cmp_ge_i32_e32 vcc, v134, v44
	s_waitcnt lgkmcnt(0)
	v_mfma_f32_16x16x32_bf16 v[72:75], v[60:63], v[68:71], 0
	v_cndmask_b32_e32 v47, 0, v45, vcc
	v_cvt_pk_bf16_f32 v45, v48, v49
	v_cvt_pk_bf16_f32 v46, v2, v50
	v_mfma_f32_16x16x32_bf16 v[60:63], v[64:67], v[68:71], 0
	ds_read_b64_tr_b16 v[64:65], v128 offset:64
	ds_read_b64_tr_b16 v[66:67], v126 offset:64
	ds_read_b64_tr_b16 v[76:77], v128 offset:96
	ds_read_b64_tr_b16 v[78:79], v126 offset:96
	v_cvt_pk_bf16_f32 v47, v51, v47
	ds_read_b64_tr_b16 v[48:49], v128 offset:4608
	ds_read_b64_tr_b16 v[50:51], v126 offset:4608
	ds_read_b64_tr_b16 v[52:53], v128 offset:4640
	ds_read_b64_tr_b16 v[54:55], v126 offset:4640
	v_cvt_pk_bf16_f32 v44, v0, v1
	ds_read_b64_tr_b16 v[56:57], v128 offset:4672
	ds_read_b64_tr_b16 v[58:59], v126 offset:4672
	s_waitcnt lgkmcnt(0)
	v_mfma_f32_16x16x32_bf16 v[52:55], v[52:55], v[44:47], v[60:63]
	s_nop 2
	ds_read_b64_tr_b16 v[60:61], v128 offset:4704
	ds_read_b64_tr_b16 v[62:63], v126 offset:4704
	v_add_u32_e32 v0, 49, v133
	v_cvt_f32_ubyte0_e32 v0, v0
	v_mfma_f32_16x16x32_bf16 v[64:67], v[64:67], v[68:71], 0
	v_mul_f32_e32 v0, v135, v0
	v_mul_f32_e32 v0, 0x3fb8aa3b, v0
	v_exp_f32_e32 v2, v0
	v_mfma_f32_16x16x32_bf16 v[68:71], v[76:79], v[68:71], 0
	v_mfma_f32_16x16x32_bf16 v[24:27], v[24:27], v[8:11], 0
	v_mfma_f32_16x16x32_bf16 v[36:39], v[36:39], v[8:11], 0
	v_mfma_f32_16x16x32_bf16 v[8:11], v[40:43], v[8:11], 0
	v_mfma_f32_16x16x32_bf16 v[48:51], v[48:51], v[44:47], v[72:75]
	v_mfma_f32_16x16x32_bf16 v[12:15], v[12:15], v[4:7], v[20:23]
	v_mfma_f32_16x16x32_bf16 v[56:59], v[56:59], v[44:47], v[64:67]
	s_waitcnt lgkmcnt(0)
	v_mfma_f32_16x16x32_bf16 v[44:47], v[60:63], v[44:47], v[68:71]
	s_nop 4
	v_fma_f32 v22, v2, v14, v50
	v_fma_f32 v23, v2, v15, v51
	v_mfma_f32_16x16x32_bf16 v[18:21], v[16:19], v[4:7], v[24:27]
	v_mfma_f32_16x16x32_bf16 v[26:29], v[28:31], v[4:7], v[36:39]
	s_nop 1
	v_fma_f32 v24, v2, v12, v48
	v_fma_f32 v25, v2, v13, v49
	s_nop 2
	v_pk_fma_f32 v[16:17], v[2:3], v[20:21], v[54:55] op_sel_hi:[0,1,1]
	v_pk_fma_f32 v[18:19], v[2:3], v[18:19], v[52:53] op_sel_hi:[0,1,1]
	v_mfma_f32_16x16x32_bf16 v[4:7], v[32:35], v[4:7], v[8:11]
	v_fma_f32 v12, v2, v28, v58
	v_fma_f32 v13, v2, v29, v59
	s_nop 5
	v_pk_fma_f32 v[0:1], v[2:3], v[6:7], v[46:47] op_sel_hi:[0,1,1]
	v_pk_fma_f32 v[10:11], v[2:3], v[4:5], v[44:45] op_sel_hi:[0,1,1]
	v_pk_mul_f32 v[4:5], v[22:23], v[22:23]
	v_pk_mul_f32 v[6:7], v[24:25], v[24:25]
	v_pk_fma_f32 v[14:15], v[2:3], v[26:27], v[56:57] op_sel_hi:[0,1,1]
	v_pk_mov_b32 v[8:9], v[6:7], v[4:5] op_sel:[1,0]
	v_mov_b32_e32 v7, v5
	v_pk_add_f32 v[4:5], v[8:9], v[6:7]
	v_pk_mul_f32 v[6:7], v[16:17], v[16:17]
	v_pk_mul_f32 v[8:9], v[18:19], v[18:19]
	v_mul_f32_e32 v2, v10, v10
	v_pk_mov_b32 v[20:21], v[8:9], v[6:7] op_sel:[1,0]
	v_mov_b32_e32 v9, v7
	v_pk_add_f32 v[6:7], v[20:21], v[8:9]
	v_mul_f32_e32 v8, v11, v11
	v_pk_add_f32 v[4:5], v[4:5], v[4:5] op_sel:[0,1] op_sel_hi:[1,0]
	v_pk_add_f32 v[6:7], v[6:7], v[6:7] op_sel:[0,1] op_sel_hi:[1,0]
	v_mov_b32_e32 v5, v2
	v_mov_b32_e32 v7, v8
	v_mul_f32_e32 v2, v15, v15
	v_mul_f32_e32 v9, v0, v0
	v_pk_add_f32 v[4:5], v[4:5], v[6:7]
	v_pk_fma_f32 v[6:7], v[14:15], v[14:15], v[2:3] op_sel_hi:[1,1,0]
	v_mul_f32_e32 v2, v13, v13
	v_mul_f32_e32 v20, v1, v1
	v_mov_b32_e32 v7, v9
	v_pk_fma_f32 v[8:9], v[12:13], v[12:13], v[2:3] op_sel_hi:[1,1,0]
	s_nop 0
	v_mov_b32_e32 v9, v20
	v_pk_add_f32 v[6:7], v[6:7], v[8:9]
	s_nop 0
	v_pk_add_f32 v[4:5], v[4:5], v[6:7]
	s_nop 0
	v_add_f32_e32 v2, v4, v5
	ds_bpermute_b32 v4, v138, v2
	s_waitcnt lgkmcnt(0)
; __device__ __forceinline__ unsigned pk2(float lo, float hi) { const f32x2_t v = {lo, hi}; const bf16x2_t b = __builtin_convertvector(v, bf16x2_t); return __builtin_bit_cast(unsigned, b); }
; __device__ __forceinline__ float sigmoidf_(float x) { return __builtin_amdgcn_rcpf(1.0f + __expf(-x)); }
; __device__ __forceinline__ float bperm_f(int src_lane, float v) { return __builtin_bit_cast(float, __builtin_amdgcn_ds_bpermute(src_lane << 2, __builtin_bit_cast(int, v))); }
; template <int KIND>
; __device__ __forceinline__ void w_m3_core(const bf16x8 (&Qf)[4][2], const bf16x8 (&Kf)[4][2], const bf16x8 (&Sf)[4][2], const LAS bf16_t* vT, float lg,
;                                           const bf16_t* gsrc, const float* nw, bf16_t* ydst, int lo, int fq) {
;     ...
;         { const int ln = (fq << 4) | lo; ss += bperm_f(ln ^ 16, ss); ss += bperm_f(ln ^ 32, ss); }
;         const float rs = rsqrtf(ss * (1.0f / 64.0f) + EPS);
;         const size_t n = 16 * nb + lo;
; #pragma unroll
;         for (int eb = 0; eb < 4; ++eb) { const int e0 = 16 * eb + 4 * fq;
;             const unsigned long long gw_ = *(const unsigned long long*)(gsrc + n * NIN + e0); const f32x4 w4 = *(const f32x4*)(nw + e0);
;             const float g0 = __uint_as_float((unsigned)gw_ << 16), g1 = __uint_as_float((unsigned)gw_ & 0xffff0000u), g2 = __uint_as_float((unsigned)(gw_ >> 32) << 16), g3 = __uint_as_float((unsigned)(gw_ >> 32) & 0xffff0000u);
;             const float o0 = O[eb][0] * rs * w4[0] * (g0 * sigmoidf_(g0)), o1 = O[eb][1] * rs * w4[1] * (g1 * sigmoidf_(g1));
;             const float o2 = O[eb][2] * rs * w4[2] * (g2 * sigmoidf_(g2)), o3 = O[eb][3] * rs * w4[3] * (g3 * sigmoidf_(g3));
;             *(unsigned long long*)(ydst + n * DM + e0) = (unsigned long long)pk2(o0, o1) | ((unsigned long long)pk2(o2, o3) << 32); }
	v_add_f32_e32 v2, v2, v4
	ds_bpermute_b32 v4, v137, v2
	s_waitcnt lgkmcnt(0)
	v_add_f32_e32 v2, v2, v4
	v_fmamk_f32 v2, v2, 0x3c800000, v200
	v_cmp_gt_f32_e32 vcc, s29, v2
	v_mul_f32_e32 v4, 0x4b800000, v2
	s_nop 0
	v_cndmask_b32_e32 v2, v2, v4, vcc
	v_rsq_f32_e32 v2, v2
	s_nop 0
	v_mul_f32_e32 v4, 0x45800000, v2
	v_cndmask_b32_e32 v8, v2, v4, vcc
	v_mad_u64_u32 v[4:5], s[20:21], v134, s72, v[98:99]
	v_lshl_add_u64 v[20:21], v[4:5], 0, v[96:97]
	v_mov_b64_e32 v[28:29], v[246:247]
	v_mov_b64_e32 v[4:5], v[184:185]
	v_mov_b64_e32 v[6:7], v[186:187]
	v_lshlrev_b32_e32 v2, 11, v134
	v_lshl_add_u64 v[26:27], s[40:41], 0, v[2:3]
	v_pk_mul_f32 v[24:25], v[24:25], v[8:9] op_sel_hi:[1,0]
	v_pk_mul_f32 v[22:23], v[22:23], v[8:9] op_sel_hi:[1,0]
	v_pk_mul_f32 v[18:19], v[18:19], v[8:9] op_sel_hi:[1,0]
	v_pk_mul_f32 v[16:17], v[16:17], v[8:9] op_sel_hi:[1,0]
	v_pk_mul_f32 v[14:15], v[14:15], v[8:9] op_sel_hi:[1,0]
	s_waitcnt lgkmcnt(0)
	v_lshlrev_b32_e32 v30, 16, v28
	v_mul_f32_e32 v2, 0xbfb8aa3b, v30
	v_exp_f32_e32 v2, v2
	v_and_b32_e32 v31, 0xffff0000, v28
	v_lshlrev_b32_e32 v28, 16, v29
	v_and_b32_e32 v29, 0xffff0000, v29
	v_add_f32_e32 v2, 1.0, v2
	v_rcp_f32_e32 v32, v2
	v_mul_f32_e32 v2, 0xbfb8aa3b, v31
	v_exp_f32_e32 v2, v2
	v_pk_mul_f32 v[4:5], v[4:5], v[24:25]
	v_pk_mul_f32 v[6:7], v[6:7], v[22:23]
	v_add_f32_e32 v2, 1.0, v2
	v_rcp_f32_e32 v33, v2
	v_mul_f32_e32 v2, 0xbfb8aa3b, v28
	v_exp_f32_e32 v2, v2
	v_pk_mul_f32 v[24:25], v[32:33], v[30:31]
	s_nop 0
	v_pk_mul_f32 v[4:5], v[24:25], v[4:5]
	v_add_f32_e32 v2, 1.0, v2
	v_rcp_f32_e32 v24, v2
	v_mul_f32_e32 v2, 0xbfb8aa3b, v29
	v_exp_f32_e32 v2, v2
	s_nop 0
	v_add_f32_e32 v2, 1.0, v2
	v_rcp_f32_e32 v25, v2
	s_nop 0
	v_pk_mul_f32 v[22:23], v[24:25], v[28:29]
	s_nop 0
	v_pk_mul_f32 v[6:7], v[22:23], v[6:7]
	v_cvt_pk_bf16_f32 v22, v4, v5
	v_cvt_pk_bf16_f32 v23, v6, v7
	v_lshl_add_u64 v[4:5], v[26:27], 0, v[96:97]
	global_store_dwordx2 v[4:5], v[22:23], off offset:1024
	v_mov_b64_e32 v[6:7], v[248:249]
	s_nop 0
	v_mov_b64_e32 v[22:23], v[188:189]
	v_mov_b64_e32 v[24:25], v[190:191]
	s_waitcnt lgkmcnt(0)
	v_lshlrev_b32_e32 v26, 16, v6
	v_mul_f32_e32 v2, 0xbfb8aa3b, v26
	v_exp_f32_e32 v2, v2
	v_and_b32_e32 v27, 0xffff0000, v6
	v_lshlrev_b32_e32 v6, 16, v7
	v_and_b32_e32 v7, 0xffff0000, v7
	v_add_f32_e32 v2, 1.0, v2
	v_rcp_f32_e32 v28, v2
	v_mul_f32_e32 v2, 0xbfb8aa3b, v27
	v_exp_f32_e32 v2, v2
	v_pk_mul_f32 v[18:19], v[22:23], v[18:19]
	v_pk_mul_f32 v[16:17], v[24:25], v[16:17]
	v_mul_f32_e32 v24, v12, v8
	v_add_f32_e32 v2, 1.0, v2
	v_rcp_f32_e32 v29, v2
	v_mul_f32_e32 v2, 0xbfb8aa3b, v6
	v_exp_f32_e32 v2, v2
	v_pk_mul_f32 v[22:23], v[28:29], v[26:27]
	s_nop 0
	v_pk_mul_f32 v[18:19], v[22:23], v[18:19]
	v_add_f32_e32 v2, 1.0, v2
	v_rcp_f32_e32 v22, v2
	v_mul_f32_e32 v2, 0xbfb8aa3b, v7
	v_exp_f32_e32 v2, v2
	s_nop 0
	v_add_f32_e32 v2, 1.0, v2
	v_rcp_f32_e32 v23, v2
	s_nop 0
	v_pk_mul_f32 v[6:7], v[22:23], v[6:7]
	s_nop 0
	v_pk_mul_f32 v[6:7], v[6:7], v[16:17]
	v_cvt_pk_bf16_f32 v16, v18, v19
	v_cvt_pk_bf16_f32 v17, v6, v7
	global_store_dwordx2 v[4:5], v[16:17], off offset:1056
	v_mov_b64_e32 v[6:7], v[250:251]
	s_nop 0
	v_mov_b64_e32 v[16:17], v[192:193]
	v_mov_b64_e32 v[18:19], v[194:195]
	s_waitcnt lgkmcnt(0)
	v_lshlrev_b32_e32 v22, 16, v6
	v_mul_f32_e32 v2, 0xbfb8aa3b, v22
	v_exp_f32_e32 v2, v2
	v_and_b32_e32 v23, 0xffff0000, v6
	v_lshlrev_b32_e32 v25, 16, v7
	v_and_b32_e32 v7, 0xffff0000, v7
	v_add_f32_e32 v2, 1.0, v2
	v_rcp_f32_e32 v26, v2
	v_mul_f32_e32 v2, 0xbfb8aa3b, v23
	v_exp_f32_e32 v2, v2
	v_pk_mul_f32 v[14:15], v[16:17], v[14:15]
	v_mul_f32_e32 v6, v13, v8
	v_mov_b32_e32 v12, v19
	v_add_f32_e32 v2, 1.0, v2
	v_rcp_f32_e32 v27, v2
	v_mul_f32_e32 v2, 0xbfb8aa3b, v25
	v_exp_f32_e32 v2, v2
	v_pk_mul_f32 v[16:17], v[26:27], v[22:23]
	s_nop 0
	v_pk_mul_f32 v[14:15], v[16:17], v[14:15]
	v_add_f32_e32 v2, 1.0, v2
	v_rcp_f32_e32 v17, v2
	v_mul_f32_e32 v2, 0xbfb8aa3b, v7
	v_exp_f32_e32 v2, v2
	v_mov_b32_e32 v16, v18
	v_pk_mul_f32 v[16:17], v[16:17], v[24:25]
	v_mul_f32_e32 v18, v11, v8
	v_add_f32_e32 v2, 1.0, v2
	v_rcp_f32_e32 v13, v2
	s_nop 0
	v_pk_mul_f32 v[6:7], v[12:13], v[6:7]
	v_cvt_pk_bf16_f32 v12, v14, v15
	v_mov_b32_e32 v14, v16
	v_mov_b32_e32 v15, v6
	v_mov_b32_e32 v6, v17
	v_pk_mul_f32 v[6:7], v[14:15], v[6:7]
	v_mul_f32_e32 v16, v10, v8
	v_cvt_pk_bf16_f32 v13, v6, v7
	global_store_dwordx2 v[4:5], v[12:13], off offset:1088
	v_mov_b64_e32 v[6:7], v[252:253]
	s_nop 0
	v_mov_b64_e32 v[12:13], v[196:197]
	v_mov_b64_e32 v[14:15], v[198:199]
	v_mul_f32_e32 v20, v0, v8
	s_waitcnt lgkmcnt(0)
	v_lshlrev_b32_e32 v17, 16, v6
	v_lshlrev_b32_e32 v21, 16, v7
	v_mul_f32_e32 v2, 0xbfb8aa3b, v17
	v_mul_f32_e32 v0, 0xbfb8aa3b, v21
	v_exp_f32_e32 v2, v2
	v_exp_f32_e32 v0, v0
	v_and_b32_e32 v19, 0xffff0000, v6
	v_and_b32_e32 v7, 0xffff0000, v7
	v_add_f32_e32 v2, 1.0, v2
	v_add_f32_e32 v0, 1.0, v0
	v_rcp_f32_e32 v23, v2
	v_mul_f32_e32 v2, 0xbfb8aa3b, v19
	v_mov_b32_e32 v10, v13
	v_rcp_f32_e32 v13, v0
	v_mul_f32_e32 v0, 0xbfb8aa3b, v7
	v_exp_f32_e32 v2, v2
	v_exp_f32_e32 v0, v0
	v_mul_f32_e32 v6, v1, v8
	v_mov_b32_e32 v22, v12
	v_add_f32_e32 v2, 1.0, v2
	v_add_f32_e32 v0, 1.0, v0
	v_rcp_f32_e32 v11, v2
	v_rcp_f32_e32 v1, v0
	v_mov_b32_e32 v12, v14
	v_mov_b32_e32 v0, v15
	v_pk_mul_f32 v[16:17], v[22:23], v[16:17]
	v_pk_mul_f32 v[10:11], v[10:11], v[18:19]
	v_pk_mul_f32 v[12:13], v[12:13], v[20:21]
	v_pk_mul_f32 v[0:1], v[0:1], v[6:7]
	v_mov_b32_e32 v6, v16
	v_mov_b32_e32 v7, v10
	v_mov_b32_e32 v10, v17
	v_mov_b32_e32 v8, v12
	v_mov_b32_e32 v9, v0
	v_mov_b32_e32 v0, v13
	v_pk_mul_f32 v[6:7], v[6:7], v[10:11]
	v_pk_mul_f32 v[0:1], v[8:9], v[0:1]
	v_cvt_pk_bf16_f32 v6, v6, v7
	v_cvt_pk_bf16_f32 v7, v0, v1
	global_store_dwordx2 v[4:5], v[6:7], off offset:1120
	s_waitcnt lgkmcnt(0)
	s_branch .LBB0_186
